# wave groups re-synced per unit (extra barrier after/before each K-loop) so both groups run the unit epilogue concurrently
# speedup vs baseline: 1.0055x; 1.0041x over previous
; #define PG8_STAGE(bufoff, gbase, voff) do { _Pragma("unroll") for (int _i = 0; _i < 2; ++_i) \
;         __builtin_amdgcn_global_load_lds((const unsigned*)((const char*)(gbase) + (voff)[_i]), (LAS unsigned*)(lds + (bufoff) + ldsw + _i * 8192), 16, 0, 0); } while (0)
; #define PG8_BAR __builtin_amdgcn_s_barrier()
; template <class Prog>
; __device__ __forceinline__ void gemm_phase(LAS unsigned char* lds, const int K, const Prog& S) {
;     ...
;     const int tid = tid_, wid = __builtin_amdgcn_readfirstlane(tid >> 6), lane = tid & 63, wr = wid >> 2, wc = wid & 3, fr = lane & 15, fq = lane >> 4;
;     const int nt = K / BK;
;     unsigned voffA[2], voffB[2];
; #pragma unroll
;     for (int i = 0; i < 2; ++i) { int R, C; stage_rc(tid * 16 + i * 8192, R, C); const int Rb = Prog::PERM ? ((R & ~31) + perm32(R & 31)) : R;
;         voffA[i] = (unsigned)(R * K + C) * 2u; voffB[i] = (unsigned)(Rb * K + C) * 2u; }
;     const size_t kstep = (size_t)(BK * 2);
;     const size_t hstep = (size_t)HALF * K * 2;
;     const unsigned ldsw = (unsigned)wid * 1024u;
;     const int aoff = lds_byte(wr * 64 + fr, fq * 8), boff = lds_byte(wc * 32 + fr, fq * 8);
;     ...
;     Unit cur, nxt; int ui = 0;
;     if (!S.next(0, cur)) return;
;     f32x4 acc[2][2][4][2];
; #pragma unroll
;     for (int a = 0; a < 2; ++a)
; #pragma unroll
;         for (int b = 0; b < 2; ++b)
; #pragma unroll
;             for (int m = 0; m < 4; ++m)
; #pragma unroll
;                 for (int n = 0; n < 2; ++n) acc[a][b][m][n] = (f32x4){0.f, 0.f, 0.f, 0.f};
;     bf16x8 At[4][2], B0[2][2], B1[2][2];
;     const char* cA = cur.a; const char* cB = cur.b;
;     PG8_STAGE(PG8_SB(0, 0), cB, voffB); PG8_STAGE(PG8_SA(0, 0), cA, voffA); PG8_STAGE(PG8_SB(0, 1), cB + hstep, voffB); PG8_STAGE(PG8_SA(0, 1), cA + hstep, voffA);
;     if (wr == 1) PG8_BAR;
.LBB0_93:
	s_and_b64 vcc, exec, s[2:3]
	s_cbranch_vccnz .LBB0_161
	v_ashrrev_i32_e32 v1, 31, v14
	v_lshrrev_b32_e32 v1, 26, v1
	v_add_u32_e32 v1, v14, v1
	v_ashrrev_i32_e32 v8, 6, v1
	v_bfe_i32 v1, v14, 27, 1
	v_lshlrev_b32_e32 v0, 4, v14
	v_lshrrev_b32_e32 v1, 22, v1
	v_add_u32_e32 v1, v0, v1
	v_and_b32_e32 v1, 0xfffffc00, v1
	v_sub_u32_e32 v1, v0, v1
	v_lshrrev_b32_e32 v2, 4, v1
	v_bitop3_b32 v1, v2, v1, 32 bitop3:0x6c
	v_ashrrev_i32_e32 v3, 31, v1
	v_lshrrev_b32_e32 v3, 26, v3
	v_add_u32_e32 v3, v1, v3
	v_lshlrev_b32_e32 v2, 3, v8
	v_ashrrev_i32_e32 v9, 6, v3
	v_and_b32_e32 v3, 0xc0, v3
	v_and_b32_e32 v2, -16, v2
	v_sub_u32_e32 v1, v1, v3
	v_add_u32_e32 v2, v9, v2
	v_ashrrev_i16_sdwa v1, v226, sext(v1) dst_sel:DWORD dst_unused:UNUSED_PAD src0_sel:DWORD src1_sel:BYTE_0
	v_lshlrev_b32_e32 v4, 5, v8
	v_bfe_i32 v10, v1, 0, 16
	v_lshlrev_b32_e32 v1, 1, v2
	v_lshrrev_b32_e32 v3, 2, v2
	v_and_b32_e32 v5, 3, v9
	s_mov_b32 s3, 0xfffe0
	v_and_b32_e32 v4, 32, v4
	v_and_b32_e32 v1, 24, v1
	v_and_b32_e32 v3, 4, v3
	v_and_or_b32 v5, v2, s3, v5
	v_or3_b32 v1, v5, v3, v1
	v_add_lshl_u32 v3, v4, v10, 1
	v_add_u32_e32 v0, 0x2000, v0
	v_lshl_add_u32 v192, v1, 12, v3
	v_ashrrev_i32_e32 v1, 31, v0
	v_lshrrev_b32_e32 v1, 22, v1
	v_add_u32_e32 v1, v0, v1
	v_ashrrev_i32_e32 v11, 10, v1
	v_mul_i32_i24_e32 v1, 0x400, v11
	v_sub_u32_e32 v0, v0, v1
	v_lshrrev_b32_e32 v1, 4, v0
	v_bitop3_b32 v0, v1, v0, 32 bitop3:0x6c
	v_lshl_add_u32 v176, v2, 12, v3
	v_ashrrev_i32_e32 v2, 31, v0
	v_lshrrev_b32_e32 v2, 26, v2
	v_lshlrev_b32_e32 v1, 3, v11
	v_add_u32_e32 v2, v0, v2
	v_and_b32_e32 v1, -16, v1
	v_ashrrev_i32_e32 v12, 6, v2
	v_and_b32_e32 v2, 0xc0, v2
	v_add_u32_e32 v1, v12, v1
	v_sub_u32_e32 v0, v0, v2
	v_and_b32_e32 v4, 3, v12
	v_ashrrev_i16_sdwa v0, v226, sext(v0) dst_sel:DWORD dst_unused:UNUSED_PAD src0_sel:DWORD src1_sel:BYTE_0
	v_and_or_b32 v4, v1, s3, v4
	s_ashr_i32 s3, s8, 6
	v_lshlrev_b32_e32 v3, 5, v11
	v_bfe_i32 v13, v0, 0, 16
	v_lshlrev_b32_e32 v0, 1, v1
	v_lshrrev_b32_e32 v2, 2, v1
	s_lshl_b32 s80, s3, 10
	v_and_b32_e32 v3, 32, v3
	v_and_b32_e32 v0, 24, v0
	v_and_b32_e32 v2, 4, v2
	s_add_i32 s92, s80, 0
	v_or3_b32 v0, v4, v2, v0
	v_add_lshl_u32 v2, v3, v13, 1
	s_add_i32 m0, s92, 0x10000
	v_lshl_add_u32 v180, v0, 12, v2
	global_load_lds_dwordx4 v192, s[44:45]
	s_add_i32 m0, s92, 0x12000
	s_ashr_i32 s2, s8, 8
	global_load_lds_dwordx4 v180, s[44:45]
	s_mov_b32 m0, s92
	s_add_i32 s93, s92, 0x2000
	v_lshl_add_u32 v178, v1, 12, v2
	global_load_lds_dwordx4 v176, s[40:41]
	s_mov_b32 m0, s93
	s_add_u32 s4, s44, 0x80000
	global_load_lds_dwordx4 v178, s[40:41]
	s_addc_u32 s5, s45, 0
	s_add_i32 m0, s92, 0x14000
	v_mov_b32_e32 v181, v193
	global_load_lds_dwordx4 v192, s[4:5]
	s_add_i32 m0, s92, 0x16000
	v_mov_b32_e32 v177, v193
	global_load_lds_dwordx4 v180, s[4:5]
	s_add_u32 s4, s40, 0x80000
	s_addc_u32 s5, s41, 0
	s_add_i32 s55, s92, 0x4000
	s_mov_b32 m0, s55
	s_add_i32 s70, s92, 0x6000
	global_load_lds_dwordx4 v176, s[4:5]
	s_mov_b32 m0, s70
	v_mov_b32_e32 v179, v193
	global_load_lds_dwordx4 v178, s[4:5]
	s_mov_b32 s79, s69
	s_mov_b32 s85, s8
	v_lshl_add_u64 v[6:7], s[44:45], 0, v[192:193]
	v_lshl_add_u64 v[4:5], s[44:45], 0, v[180:181]
	v_lshl_add_u64 v[2:3], s[40:41], 0, v[176:177]
	s_cmp_lg_u32 s2, 1
	v_lshl_add_u64 v[0:1], s[40:41], 0, v[178:179]
	s_cbranch_scc1 .LBB0_96
; #define PG8_STAGE(bufoff, gbase, voff) do { _Pragma("unroll") for (int _i = 0; _i < 2; ++_i) \
;         __builtin_amdgcn_global_load_lds((const unsigned*)((const char*)(gbase) + (voff)[_i]), (LAS unsigned*)(lds + (bufoff) + ldsw + _i * 8192), 16, 0, 0); } while (0)
; #define PG8_WAIT_V(n) asm volatile("s_waitcnt vmcnt(" #n ")" ::: "memory")
; #define PG8_BAR __builtin_amdgcn_s_barrier()
; template <class Prog>
; __device__ __forceinline__ void gemm_phase(LAS unsigned char* lds, const int K, const Prog& S) {
;     ...
;     const int aoff = lds_byte(wr * 64 + fr, fq * 8), boff = lds_byte(wc * 32 + fr, fq * 8);
;     ...
;     PG8_WAIT_V(4); PG8_BAR;
;     PG8_STAGE(PG8_SB(1, 0), cB + kstep, voffB); PG8_STAGE(PG8_SA(1, 0), cA + kstep, voffA); PG8_STAGE(PG8_SB(1, 1), cB + hstep + kstep, voffB);
;     PG8_WAIT_V(6); PG8_BAR;
;     __device__ __forceinline__ void epi(f32x4 (&acc)[2][2][4][2], const pg8::Unit& u, int wr, int wc, int fr, int fq) const {
;     ...
;                 for (int j = 0; j < 4; ++j) ci[n][j] = exp2f(-(float)(wc * 32 + 8 * fq + 4 * n + j) * (13.287712379549449f / 127.0f)) * 0.15915494309189535f;
.LBB0_96:
	v_and_b32_e32 v15, 15, v14
	v_bfe_u32 v14, v14, 4, 2
	v_lshlrev_b32_e32 v16, 4, v14
	v_lshl_or_b32 v204, s2, 6, v15
	v_lshl_or_b32 v16, v15, 6, v16
	v_lshlrev_b32_e32 v15, 2, v15
	s_lshl_b32 s3, s3, 5
	s_lshl_b32 s4, s2, 13
	v_and_b32_e32 v17, 32, v15
	s_and_b32 s3, s3, 0x60
	s_add_i32 m0, s92, 0x18000
	v_lshl_add_u64 v[6:7], v[6:7], 0, s[96:97]
	v_bitop3_b32 v18, v16, s4, v17 bitop3:0xde
	s_lshl_b32 s4, s3, 7
	s_waitcnt vmcnt(0)
	s_barrier
	global_load_lds_dwordx4 v[6:7], off
	v_lshl_add_u64 v[4:5], v[4:5], 0, s[96:97]
	s_add_i32 m0, s92, 0x1a000
	s_add_i32 s71, s92, 0x8000
	s_add_i32 s72, s92, 0xa000
	v_bitop3_b32 v205, v16, s4, v17 bitop3:0xde
	global_load_lds_dwordx4 v[4:5], off
	v_lshl_add_u64 v[2:3], v[2:3], 0, s[96:97]
	s_mov_b32 m0, s71
	s_add_u32 s4, s44, 0x80080
	global_load_lds_dwordx4 v[2:3], off
	v_lshl_add_u64 v[0:1], v[0:1], 0, s[96:97]
	s_mov_b32 m0, s72
	s_addc_u32 s5, s45, 0
	global_load_lds_dwordx4 v[0:1], off
	s_add_i32 m0, s92, 0x1c000
	v_lshl_add_u64 v[0:1], s[4:5], 0, v[192:193]
	global_load_lds_dwordx4 v[0:1], off
	v_lshl_add_u64 v[0:1], s[4:5], 0, v[180:181]
	s_add_i32 m0, s92, 0x1e000
	v_lshl_or_b32 v206, v14, 3, s3
	global_load_lds_dwordx4 v[0:1], off
	v_cvt_f32_ubyte0_e32 v0, v206
	v_mul_f32_e32 v1, 0xbdd64706, v0
	s_mov_b32 s3, 0xc2fc0000
	v_cmp_gt_f32_e32 vcc, s3, v1
	v_or_b32_e32 v2, 1, v206
	v_cvt_f32_ubyte0_e32 v2, v2
	v_cndmask_b32_e32 v1, 0, v227, vcc
	v_fmac_f32_e32 v1, 0xbdd64706, v0
	v_mul_f32_e32 v3, 0xbdd64706, v2
	v_exp_f32_e32 v0, v1
	v_cndmask_b32_e32 v1, 0, v228, vcc
	v_cmp_gt_f32_e32 vcc, s3, v3
	s_lshl_b32 s2, s2, 8
	v_ldexp_f32 v0, v0, v1
	v_cndmask_b32_e32 v3, 0, v227, vcc
	v_fmac_f32_e32 v3, 0xbdd64706, v2
	v_exp_f32_e32 v2, v3
	v_mul_f32_e32 v207, 0.15915494, v0
	v_cndmask_b32_e32 v0, 0, v228, vcc
	s_waitcnt vmcnt(6)
	v_ldexp_f32 v0, v2, v0
	v_mul_f32_e32 v208, 0.15915494, v0
	v_or_b32_e32 v0, 2, v206
	v_cvt_f32_ubyte0_e32 v0, v0
	v_mul_f32_e32 v1, 0xbdd64706, v0
	v_cmp_gt_f32_e32 vcc, s3, v1
	v_or_b32_e32 v2, 3, v206
	v_cvt_f32_ubyte0_e32 v2, v2
	v_cndmask_b32_e32 v1, 0, v227, vcc
	v_fmac_f32_e32 v1, 0xbdd64706, v0
	v_mul_f32_e32 v3, 0xbdd64706, v2
	v_exp_f32_e32 v0, v1
	v_cndmask_b32_e32 v1, 0, v228, vcc
	v_cmp_gt_f32_e32 vcc, s3, v3
	s_add_i32 s2, s2, 0
	v_ldexp_f32 v0, v0, v1
	v_cndmask_b32_e32 v3, 0, v227, vcc
	v_fmac_f32_e32 v3, 0xbdd64706, v2
	v_exp_f32_e32 v2, v3
	v_mul_f32_e32 v209, 0.15915494, v0
	v_cndmask_b32_e32 v0, 0, v228, vcc
	s_add_i32 s2, s2, 0x20000
	v_ldexp_f32 v0, v2, v0
	v_mul_f32_e32 v210, 0.15915494, v0
	v_or_b32_e32 v0, 4, v206
	v_cvt_f32_ubyte0_e32 v0, v0
	v_mul_f32_e32 v1, 0xbdd64706, v0
	v_cmp_gt_f32_e32 vcc, s3, v1
	v_or_b32_e32 v2, 5, v206
	v_cvt_f32_ubyte0_e32 v2, v2
	v_cndmask_b32_e32 v1, 0, v227, vcc
	v_fmac_f32_e32 v1, 0xbdd64706, v0
	v_mul_f32_e32 v3, 0xbdd64706, v2
	v_exp_f32_e32 v0, v1
	v_cndmask_b32_e32 v1, 0, v228, vcc
	v_cmp_gt_f32_e32 vcc, s3, v3
	s_mov_b32 s73, 0
	v_ldexp_f32 v0, v0, v1
	v_cndmask_b32_e32 v3, 0, v227, vcc
	v_fmac_f32_e32 v3, 0xbdd64706, v2
	v_exp_f32_e32 v2, v3
	v_mul_f32_e32 v211, 0.15915494, v0
	v_cndmask_b32_e32 v0, 0, v228, vcc
	s_waitcnt lgkmcnt(0)
	s_ashr_i32 s74, s54, 31
	v_ldexp_f32 v0, v2, v0
	v_mul_f32_e32 v212, 0.15915494, v0
	v_or_b32_e32 v0, 6, v206
	v_cvt_f32_ubyte0_e32 v0, v0
	v_mul_f32_e32 v1, 0xbdd64706, v0
	v_cmp_gt_f32_e32 vcc, s3, v1
	v_or_b32_e32 v2, 7, v206
	v_cvt_f32_ubyte0_e32 v2, v2
	v_cndmask_b32_e32 v1, 0, v227, vcc
	v_fmac_f32_e32 v1, 0xbdd64706, v0
	v_mul_f32_e32 v3, 0xbdd64706, v2
	v_exp_f32_e32 v0, v1
	v_cndmask_b32_e32 v1, 0, v228, vcc
	v_cmp_gt_f32_e32 vcc, s3, v3
	v_add_u32_e32 v215, s2, v15
	v_ldexp_f32 v0, v0, v1
	v_cndmask_b32_e32 v3, 0, v227, vcc
	v_fmac_f32_e32 v3, 0xbdd64706, v2
	v_exp_f32_e32 v2, v3
	v_mul_f32_e32 v213, 0.15915494, v0
	v_cndmask_b32_e32 v0, 0, v228, vcc
	v_mov_b32_e32 v1, v193
	v_ldexp_f32 v0, v2, v0
	v_mul_f32_e32 v214, 0.15915494, v0
	v_lshlrev_b32_e32 v0, 5, v14
	v_lshl_add_u64 v[182:183], s[18:19], 0, v[0:1]
	v_lshlrev_b32_e32 v0, 15, v8
	v_and_b32_e32 v0, 0xffff0000, v0
	v_lshl_add_u32 v0, v9, 12, v0
	v_and_b32_e32 v1, 1, v8
	v_lshl_or_b32 v0, v1, 6, v0
	v_lshl_add_u32 v184, v10, 1, v0
	v_lshlrev_b32_e32 v0, 15, v11
	v_and_b32_e32 v0, 0xffff0000, v0
	v_lshl_add_u32 v0, v12, 12, v0
	v_and_b32_e32 v1, 1, v11
	v_lshl_or_b32 v0, v1, 6, v0
	v_mov_b32_e32 v185, v193
	v_lshl_add_u32 v186, v13, 1, v0
	v_mov_b32_e32 v187, v193
	v_add_u32_e32 v216, 0, v18
	v_readlane_b32 s62, v254, 46
	s_mov_b32 s84, 0x3a000000
	s_barrier
	s_branch .LBB0_98

; template <class Prog>
; __device__ __forceinline__ void gemm_phase(LAS unsigned char* lds, const int K, const Prog& S) {
;     ...
;     for (;;) {
;         const bool has_next = S.next(ui + 1, nxt);
;         const char* nA = has_next ? nxt.a : cA; const char* nB = has_next ? nxt.b : cB;
;         for (int t = 0; t < nt; t += 2) {
.LBB0_100:
	s_cmpk_gt_u32 s85, 0xff
	s_cbranch_scc0 .Lrs_ip_a
	s_barrier

; #define PG8_STAGE(bufoff, gbase, voff) do { _Pragma("unroll") for (int _i = 0; _i < 2; ++_i) \
;         __builtin_amdgcn_global_load_lds((const unsigned*)((const char*)(gbase) + (voff)[_i]), (LAS unsigned*)(lds + (bufoff) + ldsw + _i * 8192), 16, 0, 0); } while (0)
; #define PG8_LDA(dst, b, h) do { _Pragma("unroll") for (int m = 0; m < 4; ++m) _Pragma("unroll") for (int k = 0; k < 2; ++k) dst[m][k] = *(const LAS bf16x8*)(lds + PG8_SA(b, h) + aoff + m * 2048 + k * 1024); } while (0)
; #define PG8_LDB(dst, b, h) do { _Pragma("unroll") for (int n = 0; n < 2; ++n) _Pragma("unroll") for (int k = 0; k < 2; ++k) dst[n][k] = *(const LAS bf16x8*)(lds + PG8_SB(b, h) + boff + n * 2048 + k * 1024); } while (0)
; #define PG8_MMA(ai, bj, At, Bt) do { __builtin_amdgcn_s_setprio(1); _Pragma("unroll") for (int m = 0; m < 4; ++m) _Pragma("unroll") for (int n = 0; n < 2; ++n) _Pragma("unroll") for (int k = 0; k < 2; ++k) \
;         acc[ai][bj][m][n] = __builtin_amdgcn_mfma_f32_16x16x32_bf16(Bt[n][k], At[m][k], acc[ai][bj][m][n], 0, 0, 0); __builtin_amdgcn_s_setprio(0); } while (0)
; #define PG8_WAIT_V(n) asm volatile("s_waitcnt vmcnt(" #n ")" ::: "memory")
; #define PG8_WAIT_L(n) asm volatile("s_waitcnt lgkmcnt(" #n ")" ::: "memory")
; #define PG8_BAR __builtin_amdgcn_s_barrier()
; #define PG8_SCHED __builtin_amdgcn_sched_barrier(0)
; template <class Prog>
; __device__ __forceinline__ void gemm_phase(LAS unsigned char* lds, const int K, const Prog& S) {
;     ...
;             const bool last = (t == nt - 2);
;             const char* a1 = cA + (size_t)(t + 1) * kstep;
;             const char* a2 = last ? nA : cA + (size_t)(t + 2) * kstep; const char* b2 = last ? nB : cB + (size_t)(t + 2) * kstep;
;             const char* a3 = a2 + kstep; const char* b3 = b2 + kstep;
;             PG8_LDB(B0, 0, 0); PG8_SCHED; PG8_LDA(At, 0, 0); PG8_STAGE(PG8_SA(1, 1), a1 + hstep, voffA);
;             PG8_WAIT_L(8); PG8_BAR; PG8_WAIT_L(0); PG8_MMA(0, 0, At, B0); PG8_BAR; PG8_SCHED;
;             PG8_LDB(B1, 0, 1); PG8_STAGE(PG8_SB(0, 0), b2, voffB);
;             PG8_BAR; PG8_WAIT_L(0); PG8_MMA(0, 1, At, B1); PG8_BAR;
;             PG8_LDA(At, 0, 1); PG8_STAGE(PG8_SA(0, 0), a2, voffA);
;             PG8_BAR; PG8_WAIT_L(0); PG8_MMA(1, 0, At, B0); PG8_BAR; PG8_SCHED;
;             PG8_STAGE(PG8_SB(0, 1), b2 + hstep, voffB);
;             PG8_WAIT_V(6); PG8_BAR; PG8_MMA(1, 1, At, B1); PG8_BAR;
.LBB0_101:
	s_add_u32 s44, s40, 0xfff80080
	s_addc_u32 s45, s41, -1
	s_cmp_eq_u32 s69, 28
	s_cselect_b32 s47, s5, s45
	s_cselect_b32 s46, s4, s44
	s_cselect_b32 s45, s13, s15
	s_cselect_b32 s44, s12, s9
	s_add_u32 s76, s40, 0xfff80000
	s_addc_u32 s77, s41, -1
	ds_read_b128 v[128:131], v244
	ds_read_b128 v[132:135], v244 offset:1024
	ds_read_b128 v[136:139], v244 offset:2048
	ds_read_b128 v[140:143], v244 offset:3072
	s_add_i32 m0, s92, 0x8000
	ds_read_b128 v[188:191], v244 offset:16384
	ds_read_b128 v[196:199], v244 offset:17408
	ds_read_b128 v[200:203], v244 offset:18432
	ds_read_b128 v[218:221], v244 offset:19456
	global_load_lds_dwordx4 v184, s[76:77]
	s_add_i32 m0, s92, 0xa000
	ds_read_b128 v[144:147], v216
	ds_read_b128 v[148:151], v216 offset:1024
	ds_read_b128 v[152:155], v216 offset:2048
	ds_read_b128 v[156:159], v216 offset:3072
	global_load_lds_dwordx4 v186, s[76:77]
	s_add_i32 m0, s92, 0xc000
	ds_read_b128 v[160:163], v216 offset:4096
	ds_read_b128 v[164:167], v216 offset:5120
	ds_read_b128 v[168:171], v216 offset:6144
	ds_read_b128 v[172:175], v216 offset:7168
	global_load_lds_dwordx4 v184, s[40:41]
	s_add_i32 m0, s92, 0xe000
	s_nop 0
	global_load_lds_dwordx4 v186, s[40:41]
	s_waitcnt lgkmcnt(0)
	s_barrier
	v_mfma_f32_16x16x32_bf16 v[124:127], v[128:131], v[144:147], v[124:127]
	v_mfma_f32_16x16x32_bf16 v[116:119], v[136:139], v[144:147], v[116:119]
	v_mfma_f32_16x16x32_bf16 v[108:111], v[128:131], v[152:155], v[108:111]
	v_mfma_f32_16x16x32_bf16 v[100:103], v[136:139], v[152:155], v[100:103]
	v_mfma_f32_16x16x32_bf16 v[92:95], v[128:131], v[160:163], v[92:95]
	v_mfma_f32_16x16x32_bf16 v[84:87], v[136:139], v[160:163], v[84:87]
	v_mfma_f32_16x16x32_bf16 v[76:79], v[128:131], v[168:171], v[76:79]
	v_mfma_f32_16x16x32_bf16 v[68:71], v[136:139], v[168:171], v[68:71]
	v_mfma_f32_16x16x32_bf16 v[124:127], v[132:135], v[148:151], v[124:127]
	v_mfma_f32_16x16x32_bf16 v[116:119], v[140:143], v[148:151], v[116:119]
	v_mfma_f32_16x16x32_bf16 v[108:111], v[132:135], v[156:159], v[108:111]
	v_mfma_f32_16x16x32_bf16 v[100:103], v[140:143], v[156:159], v[100:103]
	v_mfma_f32_16x16x32_bf16 v[92:95], v[132:135], v[164:167], v[92:95]
	v_mfma_f32_16x16x32_bf16 v[84:87], v[140:143], v[164:167], v[84:87]
	v_mfma_f32_16x16x32_bf16 v[76:79], v[132:135], v[172:175], v[76:79]
	v_mfma_f32_16x16x32_bf16 v[68:71], v[140:143], v[172:175], v[68:71]
	v_mfma_f32_16x16x32_bf16 v[120:123], v[188:191], v[144:147], v[120:123]
	v_mfma_f32_16x16x32_bf16 v[112:115], v[200:203], v[144:147], v[112:115]
	v_mfma_f32_16x16x32_bf16 v[104:107], v[188:191], v[152:155], v[104:107]
	v_mfma_f32_16x16x32_bf16 v[96:99], v[200:203], v[152:155], v[96:99]
	v_mfma_f32_16x16x32_bf16 v[88:91], v[188:191], v[160:163], v[88:91]
	v_mfma_f32_16x16x32_bf16 v[80:83], v[200:203], v[160:163], v[80:83]
	v_mfma_f32_16x16x32_bf16 v[72:75], v[188:191], v[168:171], v[72:75]
	v_mfma_f32_16x16x32_bf16 v[64:67], v[200:203], v[168:171], v[64:67]
	v_mfma_f32_16x16x32_bf16 v[120:123], v[196:199], v[148:151], v[120:123]
	v_mfma_f32_16x16x32_bf16 v[112:115], v[218:221], v[148:151], v[112:115]
	v_mfma_f32_16x16x32_bf16 v[104:107], v[196:199], v[156:159], v[104:107]
	v_mfma_f32_16x16x32_bf16 v[96:99], v[218:221], v[156:159], v[96:99]
	v_mfma_f32_16x16x32_bf16 v[88:91], v[196:199], v[164:167], v[88:91]
	v_mfma_f32_16x16x32_bf16 v[80:83], v[218:221], v[164:167], v[80:83]
	v_mfma_f32_16x16x32_bf16 v[72:75], v[196:199], v[172:175], v[72:75]
	v_mfma_f32_16x16x32_bf16 v[64:67], v[218:221], v[172:175], v[64:67]
	s_barrier
	ds_read_b128 v[144:147], v216 offset:16384
	ds_read_b128 v[148:151], v216 offset:17408
	ds_read_b128 v[152:155], v216 offset:18432
	ds_read_b128 v[156:159], v216 offset:19456
	s_add_i32 m0, s92, 0x10000
	ds_read_b128 v[160:163], v216 offset:20480
	ds_read_b128 v[164:167], v216 offset:21504
	ds_read_b128 v[168:171], v216 offset:22528
	ds_read_b128 v[172:175], v216 offset:23552
	global_load_lds_dwordx4 v192, s[44:45]
	s_add_i32 m0, s92, 0x12000
	s_nop 0
	global_load_lds_dwordx4 v180, s[44:45]
	s_add_u32 s76, s44, 0x80000
	s_addc_u32 s77, s45, 0
	s_add_i32 m0, s92, 0x14000
	s_nop 0
	global_load_lds_dwordx4 v192, s[76:77]
	s_add_i32 m0, s92, 0x16000
	s_nop 0
	global_load_lds_dwordx4 v180, s[76:77]
	s_waitcnt vmcnt(4)
	s_waitcnt lgkmcnt(0)
	s_barrier
	v_mfma_f32_16x16x32_bf16 v[60:63], v[128:131], v[144:147], v[60:63]
	v_mfma_f32_16x16x32_bf16 v[52:55], v[136:139], v[144:147], v[52:55]
	v_mfma_f32_16x16x32_bf16 v[44:47], v[128:131], v[152:155], v[44:47]
	v_mfma_f32_16x16x32_bf16 v[36:39], v[136:139], v[152:155], v[36:39]
	v_mfma_f32_16x16x32_bf16 v[28:31], v[128:131], v[160:163], v[28:31]
	v_mfma_f32_16x16x32_bf16 v[20:23], v[136:139], v[160:163], v[20:23]
	v_mfma_f32_16x16x32_bf16 v[12:15], v[128:131], v[168:171], v[12:15]
	v_mfma_f32_16x16x32_bf16 v[4:7], v[136:139], v[168:171], v[4:7]
	v_mfma_f32_16x16x32_bf16 v[60:63], v[132:135], v[148:151], v[60:63]
	v_mfma_f32_16x16x32_bf16 v[52:55], v[140:143], v[148:151], v[52:55]
	v_mfma_f32_16x16x32_bf16 v[44:47], v[132:135], v[156:159], v[44:47]
	v_mfma_f32_16x16x32_bf16 v[36:39], v[140:143], v[156:159], v[36:39]
	v_mfma_f32_16x16x32_bf16 v[28:31], v[132:135], v[164:167], v[28:31]
	v_mfma_f32_16x16x32_bf16 v[20:23], v[140:143], v[164:167], v[20:23]
	v_mfma_f32_16x16x32_bf16 v[12:15], v[132:135], v[172:175], v[12:15]
	v_mfma_f32_16x16x32_bf16 v[4:7], v[140:143], v[172:175], v[4:7]
	v_mfma_f32_16x16x32_bf16 v[56:59], v[188:191], v[144:147], v[56:59]
	v_mfma_f32_16x16x32_bf16 v[48:51], v[200:203], v[144:147], v[48:51]
	v_mfma_f32_16x16x32_bf16 v[40:43], v[188:191], v[152:155], v[40:43]
	v_mfma_f32_16x16x32_bf16 v[32:35], v[200:203], v[152:155], v[32:35]
	v_mfma_f32_16x16x32_bf16 v[24:27], v[188:191], v[160:163], v[24:27]
	v_mfma_f32_16x16x32_bf16 v[16:19], v[200:203], v[160:163], v[16:19]
	v_mfma_f32_16x16x32_bf16 v[8:11], v[188:191], v[168:171], v[8:11]
	v_mfma_f32_16x16x32_bf16 v[0:3], v[200:203], v[168:171], v[0:3]
	v_mfma_f32_16x16x32_bf16 v[56:59], v[196:199], v[148:151], v[56:59]
	v_mfma_f32_16x16x32_bf16 v[48:51], v[218:221], v[148:151], v[48:51]
	v_mfma_f32_16x16x32_bf16 v[40:43], v[196:199], v[156:159], v[40:43]
	v_mfma_f32_16x16x32_bf16 v[32:35], v[218:221], v[156:159], v[32:35]
	v_mfma_f32_16x16x32_bf16 v[24:27], v[196:199], v[164:167], v[24:27]
	v_mfma_f32_16x16x32_bf16 v[16:19], v[218:221], v[164:167], v[16:19]
	v_mfma_f32_16x16x32_bf16 v[8:11], v[196:199], v[172:175], v[8:11]
	v_mfma_f32_16x16x32_bf16 v[0:3], v[218:221], v[172:175], v[0:3]
	s_barrier
; #define PG8_STAGE(bufoff, gbase, voff) do { _Pragma("unroll") for (int _i = 0; _i < 2; ++_i) \
;         __builtin_amdgcn_global_load_lds((const unsigned*)((const char*)(gbase) + (voff)[_i]), (LAS unsigned*)(lds + (bufoff) + ldsw + _i * 8192), 16, 0, 0); } while (0)
; #define PG8_LDA(dst, b, h) do { _Pragma("unroll") for (int m = 0; m < 4; ++m) _Pragma("unroll") for (int k = 0; k < 2; ++k) dst[m][k] = *(const LAS bf16x8*)(lds + PG8_SA(b, h) + aoff + m * 2048 + k * 1024); } while (0)
; #define PG8_LDB(dst, b, h) do { _Pragma("unroll") for (int n = 0; n < 2; ++n) _Pragma("unroll") for (int k = 0; k < 2; ++k) dst[n][k] = *(const LAS bf16x8*)(lds + PG8_SB(b, h) + boff + n * 2048 + k * 1024); } while (0)
; #define PG8_MMA(ai, bj, At, Bt) do { __builtin_amdgcn_s_setprio(1); _Pragma("unroll") for (int m = 0; m < 4; ++m) _Pragma("unroll") for (int n = 0; n < 2; ++n) _Pragma("unroll") for (int k = 0; k < 2; ++k) \
;         acc[ai][bj][m][n] = __builtin_amdgcn_mfma_f32_16x16x32_bf16(Bt[n][k], At[m][k], acc[ai][bj][m][n], 0, 0, 0); __builtin_amdgcn_s_setprio(0); } while (0)
; #define PG8_WAIT_V(n) asm volatile("s_waitcnt vmcnt(" #n ")" ::: "memory")
; #define PG8_WAIT_L(n) asm volatile("s_waitcnt lgkmcnt(" #n ")" ::: "memory")
; #define PG8_BAR __builtin_amdgcn_s_barrier()
; #define PG8_SCHED __builtin_amdgcn_sched_barrier(0)
; template <class Prog>
; __device__ __forceinline__ void gemm_phase(LAS unsigned char* lds, const int K, const Prog& S) {
;     ...
;             PG8_LDB(B0, 1, 0); PG8_SCHED; PG8_LDA(At, 1, 0); PG8_STAGE(PG8_SA(0, 1), a2 + hstep, voffA);
;             PG8_WAIT_L(8); PG8_BAR; PG8_WAIT_L(0); PG8_MMA(0, 0, At, B0); PG8_BAR; PG8_SCHED;
;             PG8_LDB(B1, 1, 1); PG8_STAGE(PG8_SB(1, 0), b3, voffB);
;             PG8_BAR; PG8_WAIT_L(0); PG8_MMA(0, 1, At, B1); PG8_BAR;
;             PG8_LDA(At, 1, 1); PG8_STAGE(PG8_SA(1, 0), a3, voffA);
;             PG8_BAR; PG8_WAIT_L(0); PG8_MMA(1, 0, At, B0); PG8_BAR; PG8_SCHED;
;             PG8_STAGE(PG8_SB(1, 1), b3 + hstep, voffB);
;             PG8_WAIT_V(6); PG8_BAR; PG8_MMA(1, 1, At, B1); PG8_BAR;
;     __device__ __forceinline__ void epi(f32x4 (&acc)[2][2][4][2], const pg8::Unit& u, int wr, int wc, int fr, int fq) const {
;     ...
;         const int mode = (pn < 8) ? 1 : ((pn >= 12 && pn < 16) || (pn >= 20 && pn < 24) || (pn >= 30 && pn < 34)) ? 2 : (pn >= 34 ? 3 : 0);
	s_add_u32 s76, s46, 0x80000
	s_addc_u32 s77, s47, 0
	ds_read_b128 v[128:131], v244 offset:32768
	ds_read_b128 v[132:135], v244 offset:33792
	ds_read_b128 v[136:139], v244 offset:34816
	ds_read_b128 v[140:143], v244 offset:35840
	s_mov_b32 m0, s92
	ds_read_b128 v[188:191], v244 offset:49152
	ds_read_b128 v[196:199], v244 offset:50176
	ds_read_b128 v[200:203], v244 offset:51200
	ds_read_b128 v[218:221], v244 offset:52224
	global_load_lds_dwordx4 v176, s[46:47]
	s_add_i32 m0, s92, 0x2000
	ds_read_b128 v[144:147], v216 offset:32768
	ds_read_b128 v[148:151], v216 offset:33792
	ds_read_b128 v[152:155], v216 offset:34816
	ds_read_b128 v[156:159], v216 offset:35840
	global_load_lds_dwordx4 v178, s[46:47]
	s_add_i32 m0, s92, 0x4000
	ds_read_b128 v[160:163], v216 offset:36864
	ds_read_b128 v[164:167], v216 offset:37888
	ds_read_b128 v[168:171], v216 offset:38912
	ds_read_b128 v[172:175], v216 offset:39936
	global_load_lds_dwordx4 v176, s[76:77]
	s_add_i32 m0, s92, 0x6000
	s_nop 0
	global_load_lds_dwordx4 v178, s[76:77]
	s_waitcnt lgkmcnt(0)
	s_barrier
	v_mfma_f32_16x16x32_bf16 v[124:127], v[128:131], v[144:147], v[124:127]
	v_mfma_f32_16x16x32_bf16 v[116:119], v[136:139], v[144:147], v[116:119]
	v_mfma_f32_16x16x32_bf16 v[108:111], v[128:131], v[152:155], v[108:111]
	v_mfma_f32_16x16x32_bf16 v[100:103], v[136:139], v[152:155], v[100:103]
	v_mfma_f32_16x16x32_bf16 v[92:95], v[128:131], v[160:163], v[92:95]
	v_mfma_f32_16x16x32_bf16 v[84:87], v[136:139], v[160:163], v[84:87]
	v_mfma_f32_16x16x32_bf16 v[76:79], v[128:131], v[168:171], v[76:79]
	v_mfma_f32_16x16x32_bf16 v[68:71], v[136:139], v[168:171], v[68:71]
	v_mfma_f32_16x16x32_bf16 v[124:127], v[132:135], v[148:151], v[124:127]
	v_mfma_f32_16x16x32_bf16 v[116:119], v[140:143], v[148:151], v[116:119]
	v_mfma_f32_16x16x32_bf16 v[108:111], v[132:135], v[156:159], v[108:111]
	v_mfma_f32_16x16x32_bf16 v[100:103], v[140:143], v[156:159], v[100:103]
	v_mfma_f32_16x16x32_bf16 v[92:95], v[132:135], v[164:167], v[92:95]
	v_mfma_f32_16x16x32_bf16 v[84:87], v[140:143], v[164:167], v[84:87]
	v_mfma_f32_16x16x32_bf16 v[76:79], v[132:135], v[172:175], v[76:79]
	v_mfma_f32_16x16x32_bf16 v[68:71], v[140:143], v[172:175], v[68:71]
	v_mfma_f32_16x16x32_bf16 v[120:123], v[188:191], v[144:147], v[120:123]
	v_mfma_f32_16x16x32_bf16 v[112:115], v[200:203], v[144:147], v[112:115]
	v_mfma_f32_16x16x32_bf16 v[104:107], v[188:191], v[152:155], v[104:107]
	v_mfma_f32_16x16x32_bf16 v[96:99], v[200:203], v[152:155], v[96:99]
	v_mfma_f32_16x16x32_bf16 v[88:91], v[188:191], v[160:163], v[88:91]
	v_mfma_f32_16x16x32_bf16 v[80:83], v[200:203], v[160:163], v[80:83]
	v_mfma_f32_16x16x32_bf16 v[72:75], v[188:191], v[168:171], v[72:75]
	v_mfma_f32_16x16x32_bf16 v[64:67], v[200:203], v[168:171], v[64:67]
	v_mfma_f32_16x16x32_bf16 v[120:123], v[196:199], v[148:151], v[120:123]
	v_mfma_f32_16x16x32_bf16 v[112:115], v[218:221], v[148:151], v[112:115]
	v_mfma_f32_16x16x32_bf16 v[104:107], v[196:199], v[156:159], v[104:107]
	v_mfma_f32_16x16x32_bf16 v[96:99], v[218:221], v[156:159], v[96:99]
	v_mfma_f32_16x16x32_bf16 v[88:91], v[196:199], v[164:167], v[88:91]
	v_mfma_f32_16x16x32_bf16 v[80:83], v[218:221], v[164:167], v[80:83]
	v_mfma_f32_16x16x32_bf16 v[72:75], v[196:199], v[172:175], v[72:75]
	v_mfma_f32_16x16x32_bf16 v[64:67], v[218:221], v[172:175], v[64:67]
	s_barrier
	s_add_u32 s76, s44, 0x80
	s_addc_u32 s77, s45, 0
	ds_read_b128 v[144:147], v216 offset:49152
	ds_read_b128 v[148:151], v216 offset:50176
	ds_read_b128 v[152:155], v216 offset:51200
	ds_read_b128 v[156:159], v216 offset:52224
	s_add_i32 m0, s92, 0x18000
	ds_read_b128 v[160:163], v216 offset:53248
	ds_read_b128 v[164:167], v216 offset:54272
	ds_read_b128 v[168:171], v216 offset:55296
	ds_read_b128 v[172:175], v216 offset:56320
	global_load_lds_dwordx4 v192, s[76:77]
	s_add_i32 m0, s92, 0x1a000
	s_nop 0
	global_load_lds_dwordx4 v180, s[76:77]
	s_add_u32 s76, s44, 0x80080
	s_addc_u32 s77, s45, 0
	s_add_i32 m0, s92, 0x1c000
	s_nop 0
	global_load_lds_dwordx4 v192, s[76:77]
	s_add_i32 m0, s92, 0x1e000
	s_nop 0
	global_load_lds_dwordx4 v180, s[76:77]
	s_waitcnt vmcnt(4)
	s_waitcnt lgkmcnt(0)
	s_barrier
	v_mfma_f32_16x16x32_bf16 v[60:63], v[128:131], v[144:147], v[60:63]
	v_mfma_f32_16x16x32_bf16 v[52:55], v[136:139], v[144:147], v[52:55]
	v_mfma_f32_16x16x32_bf16 v[44:47], v[128:131], v[152:155], v[44:47]
	v_mfma_f32_16x16x32_bf16 v[36:39], v[136:139], v[152:155], v[36:39]
	v_mfma_f32_16x16x32_bf16 v[28:31], v[128:131], v[160:163], v[28:31]
	v_mfma_f32_16x16x32_bf16 v[20:23], v[136:139], v[160:163], v[20:23]
	v_mfma_f32_16x16x32_bf16 v[12:15], v[128:131], v[168:171], v[12:15]
	v_mfma_f32_16x16x32_bf16 v[4:7], v[136:139], v[168:171], v[4:7]
	v_mfma_f32_16x16x32_bf16 v[60:63], v[132:135], v[148:151], v[60:63]
	v_mfma_f32_16x16x32_bf16 v[52:55], v[140:143], v[148:151], v[52:55]
	v_mfma_f32_16x16x32_bf16 v[44:47], v[132:135], v[156:159], v[44:47]
	v_mfma_f32_16x16x32_bf16 v[36:39], v[140:143], v[156:159], v[36:39]
	v_mfma_f32_16x16x32_bf16 v[28:31], v[132:135], v[164:167], v[28:31]
	v_mfma_f32_16x16x32_bf16 v[20:23], v[140:143], v[164:167], v[20:23]
	v_mfma_f32_16x16x32_bf16 v[12:15], v[132:135], v[172:175], v[12:15]
	v_mfma_f32_16x16x32_bf16 v[4:7], v[140:143], v[172:175], v[4:7]
	v_mfma_f32_16x16x32_bf16 v[56:59], v[188:191], v[144:147], v[56:59]
	v_mfma_f32_16x16x32_bf16 v[48:51], v[200:203], v[144:147], v[48:51]
	v_mfma_f32_16x16x32_bf16 v[40:43], v[188:191], v[152:155], v[40:43]
	v_mfma_f32_16x16x32_bf16 v[32:35], v[200:203], v[152:155], v[32:35]
	v_mfma_f32_16x16x32_bf16 v[24:27], v[188:191], v[160:163], v[24:27]
	v_mfma_f32_16x16x32_bf16 v[16:19], v[200:203], v[160:163], v[16:19]
	v_mfma_f32_16x16x32_bf16 v[8:11], v[188:191], v[168:171], v[8:11]
	v_mfma_f32_16x16x32_bf16 v[0:3], v[200:203], v[168:171], v[0:3]
	v_mfma_f32_16x16x32_bf16 v[56:59], v[196:199], v[148:151], v[56:59]
	v_mfma_f32_16x16x32_bf16 v[48:51], v[218:221], v[148:151], v[48:51]
	v_mfma_f32_16x16x32_bf16 v[40:43], v[196:199], v[156:159], v[40:43]
	v_mfma_f32_16x16x32_bf16 v[32:35], v[218:221], v[156:159], v[32:35]
	v_mfma_f32_16x16x32_bf16 v[24:27], v[196:199], v[164:167], v[24:27]
	v_mfma_f32_16x16x32_bf16 v[16:19], v[218:221], v[164:167], v[16:19]
	v_mfma_f32_16x16x32_bf16 v[8:11], v[196:199], v[172:175], v[8:11]
	v_mfma_f32_16x16x32_bf16 v[0:3], v[218:221], v[172:175], v[0:3]
	s_add_i32 s69, s69, 2
	s_add_u32 s40, s40, 0x100
	s_addc_u32 s41, s41, 0
	s_add_u32 s9, s9, 0x100
	s_addc_u32 s15, s15, 0
	s_cmp_gt_u32 s69, 29
	s_barrier
	s_cbranch_scc0 .LBB0_101
	s_cmpk_gt_u32 s85, 0xff
	s_cbranch_scc1 .Lrs_ip_b
	s_barrier
.Lrs_ip_b:
	s_cmp_lt_i32 s75, 8
	s_mov_b32 s9, 1
	s_cbranch_scc1 .LBB0_110
	s_sub_i32 s4, s75, 30
	s_cmp_lt_u32 s4, 4
	s_mov_b32 s9, 2
	s_cbranch_scc1 .LBB0_110
	s_and_b32 s9, s75, 0x7ffffffc
	s_cmp_lt_i32 s9, 20
	s_cbranch_scc1 .LBB0_106
	s_cmp_lg_u32 s9, 20
	s_cselect_b64 s[4:5], -1, 0
	s_cbranch_execz .LBB0_107
	s_branch .LBB0_108

; #define PG8_WAIT_V(n) asm volatile("s_waitcnt vmcnt(" #n ")" ::: "memory")
; #define PG8_BAR __builtin_amdgcn_s_barrier()
; template <class Prog>
; __device__ __forceinline__ void gemm_phase(LAS unsigned char* lds, const int K, const Prog& S) {
;     ...
;     PG8_WAIT_V(0);
;     if (wr == 0) PG8_BAR;
;     PG8_BAR;
.LBB0_158:
	s_waitcnt vmcnt(0)
	s_cmpk_gt_u32 s85, 0xff
	s_mov_b32 s69, s79
	s_cbranch_scc1 .LBB0_160
.LBB0_160:
	v_readlane_b32 s76, v254, 0
	v_readlane_b32 s78, v255, 11
	v_readlane_b32 s82, v255, 13
	v_readlane_b32 s84, v255, 15
	v_readlane_b32 s92, v255, 17
	v_readlane_b32 s94, v255, 19
	v_readlane_b32 s72, v255, 21
	v_readlane_b32 s70, v255, 23
	v_readlane_b32 s77, v254, 1
	v_readlane_b32 s79, v255, 12
	v_readlane_b32 s83, v255, 14
	v_readlane_b32 s85, v255, 16
	v_readlane_b32 s93, v255, 18
	v_readlane_b32 s95, v255, 20
	v_readlane_b32 s73, v255, 22
	v_readlane_b32 s71, v255, 24
	s_mov_b32 s62, 0x3fb8aa3b
	s_barrier

; #define PG8_STAGE(bufoff, gbase, voff) do { _Pragma("unroll") for (int _i = 0; _i < 2; ++_i) \
;         __builtin_amdgcn_global_load_lds((const unsigned*)((const char*)(gbase) + (voff)[_i]), (LAS unsigned*)(lds + (bufoff) + ldsw + _i * 8192), 16, 0, 0); } while (0)
; #define PG8_BAR __builtin_amdgcn_s_barrier()
; template <class Prog>
; __device__ __forceinline__ void gemm_phase(LAS unsigned char* lds, const int K, const Prog& S) {
;     ...
;     const int tid = tid_, wid = __builtin_amdgcn_readfirstlane(tid >> 6), lane = tid & 63, wr = wid >> 2, wc = wid & 3, fr = lane & 15, fq = lane >> 4;
;     const int nt = K / BK;
;     unsigned voffA[2], voffB[2];
; #pragma unroll
;     for (int i = 0; i < 2; ++i) { int R, C; stage_rc(tid * 16 + i * 8192, R, C); const int Rb = Prog::PERM ? ((R & ~31) + perm32(R & 31)) : R;
;         voffA[i] = (unsigned)(R * K + C) * 2u; voffB[i] = (unsigned)(Rb * K + C) * 2u; }
;     const size_t kstep = (size_t)(BK * 2);
;     const size_t hstep = (size_t)HALF * K * 2;
;     const unsigned ldsw = (unsigned)wid * 1024u;
;     const int aoff = lds_byte(wr * 64 + fr, fq * 8), boff = lds_byte(wc * 32 + fr, fq * 8);
;     ...
;     Unit cur, nxt; int ui = 0;
;     if (!S.next(0, cur)) return;
;     f32x4 acc[2][2][4][2];
; #pragma unroll
;     for (int a = 0; a < 2; ++a)
; #pragma unroll
;         for (int b = 0; b < 2; ++b)
; #pragma unroll
;             for (int m = 0; m < 4; ++m)
; #pragma unroll
;                 for (int n = 0; n < 2; ++n) acc[a][b][m][n] = (f32x4){0.f, 0.f, 0.f, 0.f};
;     bf16x8 At[4][2], B0[2][2], B1[2][2];
;     const char* cA = cur.a; const char* cB = cur.b;
;     PG8_STAGE(PG8_SB(0, 0), cB, voffB); PG8_STAGE(PG8_SA(0, 0), cA, voffA); PG8_STAGE(PG8_SB(0, 1), cB + hstep, voffB); PG8_STAGE(PG8_SA(0, 1), cA + hstep, voffA);
;     if (wr == 1) PG8_BAR;
.LBB0_392:
	s_and_b64 vcc, exec, s[2:3]
	s_cbranch_vccnz .LBB0_504
	v_bfe_i32 v2, v0, 27, 1
	v_lshlrev_b32_e32 v4, 4, v0
	v_lshrrev_b32_e32 v2, 22, v2
	s_waitcnt lgkmcnt(0)
	v_ashrrev_i32_e32 v1, 31, v0
	v_add_u32_e32 v2, v4, v2
	v_lshrrev_b32_e32 v1, 26, v1
	v_and_b32_e32 v2, 0xfffffc00, v2
	v_add_u32_e32 v1, v0, v1
	v_sub_u32_e32 v2, v4, v2
	v_ashrrev_i32_e32 v1, 6, v1
	v_lshrrev_b32_e32 v3, 4, v2
	v_bitop3_b32 v3, v3, v2, 32 bitop3:0x6c
	v_lshlrev_b32_e32 v2, 3, v1
	v_and_b32_e32 v5, -16, v2
	v_ashrrev_i32_e32 v2, 31, v3
	v_lshrrev_b32_e32 v2, 26, v2
	v_add_u32_e32 v6, v3, v2
	v_ashrrev_i32_e32 v2, 6, v6
	v_and_b32_e32 v6, 0xc0, v6
	v_sub_u32_e32 v3, v3, v6
	v_lshlrev_b32_e32 v7, 5, v1
	v_ashrrev_i16_sdwa v3, v226, sext(v3) dst_sel:DWORD dst_unused:UNUSED_PAD src0_sel:DWORD src1_sel:BYTE_0
	v_and_b32_e32 v7, 32, v7
	v_bfe_i32 v3, v3, 0, 16
	v_add_u32_e32 v5, v2, v5
	v_and_b32_e32 v9, 3, v2
	s_mov_b32 s5, 0x1fffe0
	v_add_lshl_u32 v7, v7, v3, 1
	v_lshlrev_b32_e32 v6, 1, v5
	v_lshrrev_b32_e32 v8, 2, v5
	v_and_or_b32 v9, v5, s5, v9
	v_lshl_add_u32 v196, v5, 11, v7
	v_add_u32_e32 v5, 0x2000, v4
	v_ashrrev_i32_e32 v4, 31, v5
	v_lshrrev_b32_e32 v4, 22, v4
	v_and_b32_e32 v6, 24, v6
	v_and_b32_e32 v8, 4, v8
	v_add_u32_e32 v4, v5, v4
	v_or3_b32 v6, v9, v8, v6
	v_ashrrev_i32_e32 v4, 10, v4
	v_lshl_add_u32 v192, v6, 11, v7
	v_mul_i32_i24_e32 v6, 0x400, v4
	v_sub_u32_e32 v5, v5, v6
	v_lshrrev_b32_e32 v6, 4, v5
	v_bitop3_b32 v6, v6, v5, 32 bitop3:0x6c
	v_lshlrev_b32_e32 v5, 3, v4
	v_and_b32_e32 v7, -16, v5
	v_ashrrev_i32_e32 v5, 31, v6
	v_lshrrev_b32_e32 v5, 26, v5
	v_add_u32_e32 v8, v6, v5
	v_ashrrev_i32_e32 v5, 6, v8
	v_add_u32_e32 v7, v5, v7
	v_and_b32_e32 v8, 0xc0, v8
	v_and_b32_e32 v11, 3, v5
	v_sub_u32_e32 v6, v6, v8
	v_and_or_b32 v11, v7, s5, v11
	s_ashr_i32 s5, s6, 6
	v_lshlrev_b32_e32 v9, 5, v4
	v_ashrrev_i16_sdwa v6, v226, sext(v6) dst_sel:DWORD dst_unused:UNUSED_PAD src0_sel:DWORD src1_sel:BYTE_0
	v_lshlrev_b32_e32 v8, 1, v7
	v_lshrrev_b32_e32 v10, 2, v7
	s_lshl_b32 s73, s5, 10
	v_and_b32_e32 v9, 32, v9
	v_bfe_i32 v6, v6, 0, 16
	v_and_b32_e32 v8, 24, v8
	v_and_b32_e32 v10, 4, v10
	s_add_i32 s74, s73, 0
	v_or3_b32 v8, v11, v10, v8
	v_add_lshl_u32 v9, v9, v6, 1
	s_add_i32 m0, s74, 0x10000
	s_waitcnt lgkmcnt(0)
	v_lshl_add_u32 v200, v8, 11, v9
	global_load_lds_dwordx4 v192, s[46:47]
	s_add_i32 m0, s74, 0x12000
	s_ashr_i32 s4, s6, 8
	global_load_lds_dwordx4 v200, s[46:47]
	s_mov_b32 m0, s74
	s_add_i32 s75, s74, 0x2000
	v_lshl_add_u32 v198, v7, 11, v9
	s_mov_b32 s62, s6
	global_load_lds_dwordx4 v196, s[44:45]
	s_mov_b32 m0, s75
	s_add_u32 s6, s46, 0x40000
	global_load_lds_dwordx4 v198, s[44:45]
	s_addc_u32 s7, s47, 0
	s_add_i32 m0, s74, 0x14000
	v_writelane_b32 v255, s69, 26
	global_load_lds_dwordx4 v192, s[6:7]
	s_add_i32 m0, s74, 0x16000
	s_nop 0
	global_load_lds_dwordx4 v200, s[6:7]
	s_add_u32 s6, s44, 0x40000
	s_addc_u32 s7, s45, 0
	s_add_i32 s80, s74, 0x4000
	s_mov_b32 m0, s80
	s_add_i32 s76, s74, 0x6000
	global_load_lds_dwordx4 v196, s[6:7]
	s_mov_b32 m0, s76
	s_cmp_lg_u32 s4, 1
	global_load_lds_dwordx4 v198, s[6:7]
	v_readlane_b32 s6, v254, 4
	v_readlane_b32 s7, v254, 5
	s_load_dword s77, s[6:7], 0x0
	s_cbranch_scc1 .LBB0_395
; #define PG8_STAGE(bufoff, gbase, voff) do { _Pragma("unroll") for (int _i = 0; _i < 2; ++_i) \
;         __builtin_amdgcn_global_load_lds((const unsigned*)((const char*)(gbase) + (voff)[_i]), (LAS unsigned*)(lds + (bufoff) + ldsw + _i * 8192), 16, 0, 0); } while (0)
; #define PG8_WAIT_V(n) asm volatile("s_waitcnt vmcnt(" #n ")" ::: "memory")
; #define PG8_BAR __builtin_amdgcn_s_barrier()
; template <class Prog>
; __device__ __forceinline__ void gemm_phase(LAS unsigned char* lds, const int K, const Prog& S) {
;     ...
;     const int aoff = lds_byte(wr * 64 + fr, fq * 8), boff = lds_byte(wc * 32 + fr, fq * 8);
;     ...
;     f32x4 acc[2][2][4][2];
; #pragma unroll
;     for (int a = 0; a < 2; ++a)
; #pragma unroll
;         for (int b = 0; b < 2; ++b)
; #pragma unroll
;             for (int m = 0; m < 4; ++m)
; #pragma unroll
;                 for (int n = 0; n < 2; ++n) acc[a][b][m][n] = (f32x4){0.f, 0.f, 0.f, 0.f};
;     ...
;     PG8_WAIT_V(4); PG8_BAR;
;     PG8_STAGE(PG8_SB(1, 0), cB + kstep, voffB); PG8_STAGE(PG8_SA(1, 0), cA + kstep, voffA); PG8_STAGE(PG8_SB(1, 1), cB + hstep + kstep, voffB);
;     PG8_WAIT_V(6); PG8_BAR;
.LBB0_395:
	v_lshrrev_b32_e32 v16, 1, v0
	v_and_b32_e32 v16, 24, v16
	v_and_b32_e32 v7, 15, v0
	v_lshlrev_b32_e32 v17, 1, v16
	v_lshlrev_b32_e32 v0, 2, v0
	v_lshl_or_b32 v244, s4, 6, v7
	v_lshl_or_b32 v7, v7, 6, v17
	s_lshl_b32 s4, s4, 13
	v_and_b32_e32 v0, 32, v0
	v_lshl_add_u64 v[8:9], s[46:47], 0, v[192:193]
	v_mov_b32_e32 v201, v193
	v_bitop3_b32 v17, v7, s4, v0 bitop3:0xde
	s_lshl_b32 s4, s5, 5
	v_lshl_add_u64 v[10:11], s[46:47], 0, v[200:201]
	v_mov_b32_e32 v197, v193
	s_and_b32 s6, s4, 0x60
	s_add_i32 m0, s74, 0x18000
	v_lshl_add_u64 v[8:9], v[8:9], 0, s[96:97]
	v_lshl_add_u64 v[12:13], s[44:45], 0, v[196:197]
	v_mov_b32_e32 v199, v193
	s_lshl_b32 s4, s6, 7
	s_waitcnt vmcnt(0)
	s_barrier
	global_load_lds_dwordx4 v[8:9], off
	v_lshl_add_u64 v[8:9], v[10:11], 0, s[96:97]
	s_add_i32 m0, s74, 0x1a000
	s_add_i32 s78, s74, 0x8000
	s_add_i32 s79, s74, 0xa000
	v_lshl_add_u64 v[14:15], s[44:45], 0, v[198:199]
	v_bitop3_b32 v245, v7, s4, v0 bitop3:0xde
	global_load_lds_dwordx4 v[8:9], off
	v_lshl_add_u64 v[8:9], v[12:13], 0, s[96:97]
	s_mov_b32 m0, s78
	s_add_u32 s4, s46, 0x40080
	global_load_lds_dwordx4 v[8:9], off
	v_lshl_add_u64 v[8:9], v[14:15], 0, s[96:97]
	s_mov_b32 m0, s79
	s_addc_u32 s5, s47, 0
	global_load_lds_dwordx4 v[8:9], off
	s_add_i32 m0, s74, 0x1c000
	v_lshl_add_u64 v[8:9], s[4:5], 0, v[192:193]
	global_load_lds_dwordx4 v[8:9], off
	v_lshl_add_u64 v[8:9], s[4:5], 0, v[200:201]
	s_add_i32 m0, s74, 0x1e000
	v_lshlrev_b32_e32 v0, 14, v1
	global_load_lds_dwordx4 v[8:9], off
	v_and_b32_e32 v0, 0xffff8000, v0
	v_lshl_add_u32 v0, v2, 11, v0
	v_and_b32_e32 v1, 1, v1
	v_lshl_or_b32 v0, v1, 6, v0
	v_lshl_add_u32 v202, v3, 1, v0
	v_lshlrev_b32_e32 v0, 14, v4
	v_and_b32_e32 v0, 0xffff8000, v0
	v_lshl_add_u32 v0, v5, 11, v0
	v_and_b32_e32 v1, 1, v4
	s_waitcnt vmcnt(6)
	v_lshl_or_b32 v0, v1, 6, v0
	v_lshl_add_u32 v204, v6, 1, v0
	v_mov_b32_e32 v0, 0
	v_or_b32_e32 v246, s6, v16
	v_mov_b32_e32 v203, v193
	v_mov_b32_e32 v205, v193
	s_mov_b32 s14, 0
	v_add_u32_e32 v247, 0, v17
	s_mov_b32 s72, 0
	v_mov_b32_e32 v1, v0
	v_mov_b32_e32 v2, v0
	v_mov_b32_e32 v3, v0
	v_mov_b32_e32 v4, v0
	v_mov_b32_e32 v5, v0
	v_mov_b32_e32 v6, v0
	v_mov_b32_e32 v7, v0
	v_mov_b32_e32 v8, v0
	v_mov_b32_e32 v9, v0
	v_mov_b32_e32 v10, v0
	v_mov_b32_e32 v11, v0
	v_mov_b32_e32 v12, v0
	v_mov_b32_e32 v13, v0
	v_mov_b32_e32 v14, v0
	v_mov_b32_e32 v15, v0
	v_mov_b32_e32 v16, v0
	v_mov_b32_e32 v17, v0
	v_mov_b32_e32 v18, v0
	v_mov_b32_e32 v19, v0
	v_mov_b32_e32 v20, v0
	v_mov_b32_e32 v21, v0
	v_mov_b32_e32 v22, v0
	v_mov_b32_e32 v23, v0
	s_waitcnt vmcnt(0)
	v_mov_b32_e32 v24, v0
	v_mov_b32_e32 v25, v0
	v_mov_b32_e32 v26, v0
	v_mov_b32_e32 v27, v0
	v_mov_b32_e32 v28, v0
	v_mov_b32_e32 v29, v0
	v_mov_b32_e32 v30, v0
	v_mov_b32_e32 v31, v0
	v_mov_b32_e32 v32, v0
	v_mov_b32_e32 v33, v0
	v_mov_b32_e32 v34, v0
	v_mov_b32_e32 v35, v0
	v_mov_b32_e32 v36, v0
	v_mov_b32_e32 v37, v0
	v_mov_b32_e32 v38, v0
	v_mov_b32_e32 v39, v0
	v_mov_b32_e32 v40, v0
	v_mov_b32_e32 v41, v0
	v_mov_b32_e32 v42, v0
	v_mov_b32_e32 v43, v0
	v_mov_b32_e32 v44, v0
	v_mov_b32_e32 v45, v0
	v_mov_b32_e32 v46, v0
	v_mov_b32_e32 v47, v0
	v_mov_b32_e32 v48, v0
	v_mov_b32_e32 v49, v0
	v_mov_b32_e32 v50, v0
	v_mov_b32_e32 v51, v0
	v_mov_b32_e32 v52, v0
	v_mov_b32_e32 v53, v0
	v_mov_b32_e32 v54, v0
	v_mov_b32_e32 v55, v0
	v_mov_b32_e32 v56, v0
	v_mov_b32_e32 v57, v0
	v_mov_b32_e32 v58, v0
	v_mov_b32_e32 v59, v0
	v_mov_b32_e32 v60, v0
	v_mov_b32_e32 v61, v0
	v_mov_b32_e32 v62, v0
	v_mov_b32_e32 v63, v0
	v_mov_b32_e32 v64, v0
	v_mov_b32_e32 v65, v0
	v_mov_b32_e32 v66, v0
	v_mov_b32_e32 v67, v0
	v_mov_b32_e32 v68, v0
	v_mov_b32_e32 v69, v0
	v_mov_b32_e32 v70, v0
	v_mov_b32_e32 v71, v0
	v_mov_b32_e32 v72, v0
	v_mov_b32_e32 v73, v0
	v_mov_b32_e32 v74, v0
	v_mov_b32_e32 v75, v0
	v_mov_b32_e32 v76, v0
	v_mov_b32_e32 v77, v0
	v_mov_b32_e32 v78, v0
	v_mov_b32_e32 v79, v0
	v_mov_b32_e32 v80, v0
	v_mov_b32_e32 v81, v0
	v_mov_b32_e32 v82, v0
	v_mov_b32_e32 v83, v0
	v_mov_b32_e32 v84, v0
	v_mov_b32_e32 v85, v0
	v_mov_b32_e32 v86, v0
	v_mov_b32_e32 v87, v0
	v_mov_b32_e32 v88, v0
	v_mov_b32_e32 v89, v0
	v_mov_b32_e32 v90, v0
	v_mov_b32_e32 v91, v0
	v_mov_b32_e32 v92, v0
	v_mov_b32_e32 v93, v0
	v_mov_b32_e32 v94, v0
	v_mov_b32_e32 v95, v0
	v_mov_b32_e32 v96, v0
	v_mov_b32_e32 v97, v0
	v_mov_b32_e32 v98, v0
	v_mov_b32_e32 v99, v0
	v_mov_b32_e32 v100, v0
	v_mov_b32_e32 v101, v0
	v_mov_b32_e32 v102, v0
	v_mov_b32_e32 v103, v0
	v_mov_b32_e32 v104, v0
	v_mov_b32_e32 v105, v0
	v_mov_b32_e32 v106, v0
	v_mov_b32_e32 v107, v0
	v_mov_b32_e32 v108, v0
	v_mov_b32_e32 v109, v0
	v_mov_b32_e32 v110, v0
	v_mov_b32_e32 v111, v0
	v_mov_b32_e32 v112, v0
	v_mov_b32_e32 v113, v0
	v_mov_b32_e32 v114, v0
	v_mov_b32_e32 v115, v0
	v_mov_b32_e32 v116, v0
	v_mov_b32_e32 v117, v0
	v_mov_b32_e32 v118, v0
	v_mov_b32_e32 v119, v0
	v_mov_b32_e32 v120, v0
	v_mov_b32_e32 v121, v0
	v_mov_b32_e32 v122, v0
	v_mov_b32_e32 v123, v0
	v_mov_b32_e32 v124, v0
	v_mov_b32_e32 v125, v0
	v_mov_b32_e32 v126, v0
	v_mov_b32_e32 v127, v0
	s_barrier
	s_branch .LBB0_397

; template <class Prog>
; __device__ __forceinline__ void gemm_phase(LAS unsigned char* lds, const int K, const Prog& S) {
;     ...
;     for (;;) {
;         const bool has_next = S.next(ui + 1, nxt);
;         const char* nA = has_next ? nxt.a : cA; const char* nB = has_next ? nxt.b : cB;
;         for (int t = 0; t < nt; t += 2) {
.LBB0_399:
	s_cmpk_gt_u32 s62, 0xff
	s_cbranch_scc0 .Lrs_mg_a
	s_barrier

; #define PG8_STAGE(bufoff, gbase, voff) do { _Pragma("unroll") for (int _i = 0; _i < 2; ++_i) \
;         __builtin_amdgcn_global_load_lds((const unsigned*)((const char*)(gbase) + (voff)[_i]), (LAS unsigned*)(lds + (bufoff) + ldsw + _i * 8192), 16, 0, 0); } while (0)
; #define PG8_LDA(dst, b, h) do { _Pragma("unroll") for (int m = 0; m < 4; ++m) _Pragma("unroll") for (int k = 0; k < 2; ++k) dst[m][k] = *(const LAS bf16x8*)(lds + PG8_SA(b, h) + aoff + m * 2048 + k * 1024); } while (0)
; #define PG8_LDB(dst, b, h) do { _Pragma("unroll") for (int n = 0; n < 2; ++n) _Pragma("unroll") for (int k = 0; k < 2; ++k) dst[n][k] = *(const LAS bf16x8*)(lds + PG8_SB(b, h) + boff + n * 2048 + k * 1024); } while (0)
; #define PG8_MMA(ai, bj, At, Bt) do { __builtin_amdgcn_s_setprio(1); _Pragma("unroll") for (int m = 0; m < 4; ++m) _Pragma("unroll") for (int n = 0; n < 2; ++n) _Pragma("unroll") for (int k = 0; k < 2; ++k) \
;         acc[ai][bj][m][n] = __builtin_amdgcn_mfma_f32_16x16x32_bf16(Bt[n][k], At[m][k], acc[ai][bj][m][n], 0, 0, 0); __builtin_amdgcn_s_setprio(0); } while (0)
; #define PG8_WAIT_V(n) asm volatile("s_waitcnt vmcnt(" #n ")" ::: "memory")
; #define PG8_WAIT_L(n) asm volatile("s_waitcnt lgkmcnt(" #n ")" ::: "memory")
; #define PG8_BAR __builtin_amdgcn_s_barrier()
; #define PG8_SCHED __builtin_amdgcn_sched_barrier(0)
; template <class Prog>
; __device__ __forceinline__ void gemm_phase(LAS unsigned char* lds, const int K, const Prog& S) {
;     ...
;             const bool last = (t == nt - 2);
;             const char* a1 = cA + (size_t)(t + 1) * kstep;
;             const char* a2 = last ? nA : cA + (size_t)(t + 2) * kstep; const char* b2 = last ? nB : cB + (size_t)(t + 2) * kstep;
;             const char* a3 = a2 + kstep; const char* b3 = b2 + kstep;
;             PG8_LDB(B0, 0, 0); PG8_SCHED; PG8_LDA(At, 0, 0); PG8_STAGE(PG8_SA(1, 1), a1 + hstep, voffA);
;             PG8_WAIT_L(8); PG8_BAR; PG8_WAIT_L(0); PG8_MMA(0, 0, At, B0); PG8_BAR; PG8_SCHED;
;             PG8_LDB(B1, 0, 1); PG8_STAGE(PG8_SB(0, 0), b2, voffB);
;             PG8_BAR; PG8_WAIT_L(0); PG8_MMA(0, 1, At, B1); PG8_BAR;
;             PG8_LDA(At, 0, 1); PG8_STAGE(PG8_SA(0, 0), a2, voffA);
;             PG8_BAR; PG8_WAIT_L(0); PG8_MMA(1, 0, At, B0); PG8_BAR; PG8_SCHED;
;             PG8_STAGE(PG8_SB(0, 1), b2 + hstep, voffB);
;             PG8_WAIT_V(6); PG8_BAR; PG8_MMA(1, 1, At, B1); PG8_BAR;
.LBB0_400:
	s_add_u32 s46, s44, 0xfffc0080
	s_addc_u32 s47, s45, -1
	s_cmp_eq_u32 s55, 12
	s_cselect_b32 s53, s7, s47
	s_cselect_b32 s52, s6, s46
	s_cselect_b32 s47, s9, s43
	s_cselect_b32 s46, s8, s41
	s_add_u32 s84, s44, 0xfffc0000
	s_addc_u32 s85, s45, -1
	ds_read_b128 v[128:131], v206
	ds_read_b128 v[132:135], v206 offset:1024
	ds_read_b128 v[136:139], v206 offset:2048
	ds_read_b128 v[140:143], v206 offset:3072
	s_add_i32 m0, s74, 0x8000
	ds_read_b128 v[176:179], v206 offset:16384
	ds_read_b128 v[180:183], v206 offset:17408
	ds_read_b128 v[184:187], v206 offset:18432
	ds_read_b128 v[188:191], v206 offset:19456
	global_load_lds_dwordx4 v202, s[84:85]
	s_add_i32 m0, s74, 0xa000
	ds_read_b128 v[144:147], v247
	ds_read_b128 v[148:151], v247 offset:1024
	ds_read_b128 v[152:155], v247 offset:2048
	ds_read_b128 v[156:159], v247 offset:3072
	global_load_lds_dwordx4 v204, s[84:85]
	s_add_i32 m0, s74, 0xc000
	ds_read_b128 v[160:163], v247 offset:4096
	ds_read_b128 v[164:167], v247 offset:5120
	ds_read_b128 v[168:171], v247 offset:6144
	ds_read_b128 v[172:175], v247 offset:7168
	global_load_lds_dwordx4 v202, s[44:45]
	s_add_i32 m0, s74, 0xe000
	s_nop 0
	global_load_lds_dwordx4 v204, s[44:45]
	s_waitcnt lgkmcnt(0)
	s_barrier
	v_mfma_f32_16x16x32_bf16 v[124:127], v[128:131], v[144:147], v[124:127]
	v_mfma_f32_16x16x32_bf16 v[120:123], v[136:139], v[144:147], v[120:123]
	v_mfma_f32_16x16x32_bf16 v[116:119], v[128:131], v[152:155], v[116:119]
	v_mfma_f32_16x16x32_bf16 v[112:115], v[136:139], v[152:155], v[112:115]
	v_mfma_f32_16x16x32_bf16 v[108:111], v[128:131], v[160:163], v[108:111]
	v_mfma_f32_16x16x32_bf16 v[104:107], v[136:139], v[160:163], v[104:107]
	v_mfma_f32_16x16x32_bf16 v[100:103], v[128:131], v[168:171], v[100:103]
	v_mfma_f32_16x16x32_bf16 v[96:99], v[136:139], v[168:171], v[96:99]
	v_mfma_f32_16x16x32_bf16 v[124:127], v[132:135], v[148:151], v[124:127]
	v_mfma_f32_16x16x32_bf16 v[120:123], v[140:143], v[148:151], v[120:123]
	v_mfma_f32_16x16x32_bf16 v[116:119], v[132:135], v[156:159], v[116:119]
	v_mfma_f32_16x16x32_bf16 v[112:115], v[140:143], v[156:159], v[112:115]
	v_mfma_f32_16x16x32_bf16 v[108:111], v[132:135], v[164:167], v[108:111]
	v_mfma_f32_16x16x32_bf16 v[104:107], v[140:143], v[164:167], v[104:107]
	v_mfma_f32_16x16x32_bf16 v[100:103], v[132:135], v[172:175], v[100:103]
	v_mfma_f32_16x16x32_bf16 v[96:99], v[140:143], v[172:175], v[96:99]
	v_mfma_f32_16x16x32_bf16 v[92:95], v[176:179], v[144:147], v[92:95]
	v_mfma_f32_16x16x32_bf16 v[88:91], v[184:187], v[144:147], v[88:91]
	v_mfma_f32_16x16x32_bf16 v[84:87], v[176:179], v[152:155], v[84:87]
	v_mfma_f32_16x16x32_bf16 v[80:83], v[184:187], v[152:155], v[80:83]
	v_mfma_f32_16x16x32_bf16 v[76:79], v[176:179], v[160:163], v[76:79]
	v_mfma_f32_16x16x32_bf16 v[72:75], v[184:187], v[160:163], v[72:75]
	v_mfma_f32_16x16x32_bf16 v[68:71], v[176:179], v[168:171], v[68:71]
	v_mfma_f32_16x16x32_bf16 v[64:67], v[184:187], v[168:171], v[64:67]
	v_mfma_f32_16x16x32_bf16 v[92:95], v[180:183], v[148:151], v[92:95]
	v_mfma_f32_16x16x32_bf16 v[88:91], v[188:191], v[148:151], v[88:91]
	v_mfma_f32_16x16x32_bf16 v[84:87], v[180:183], v[156:159], v[84:87]
	v_mfma_f32_16x16x32_bf16 v[80:83], v[188:191], v[156:159], v[80:83]
	v_mfma_f32_16x16x32_bf16 v[76:79], v[180:183], v[164:167], v[76:79]
	v_mfma_f32_16x16x32_bf16 v[72:75], v[188:191], v[164:167], v[72:75]
	v_mfma_f32_16x16x32_bf16 v[68:71], v[180:183], v[172:175], v[68:71]
	v_mfma_f32_16x16x32_bf16 v[64:67], v[188:191], v[172:175], v[64:67]
	s_barrier
	ds_read_b128 v[144:147], v247 offset:16384
	ds_read_b128 v[148:151], v247 offset:17408
	ds_read_b128 v[152:155], v247 offset:18432
	ds_read_b128 v[156:159], v247 offset:19456
	s_add_i32 m0, s74, 0x10000
	ds_read_b128 v[160:163], v247 offset:20480
	ds_read_b128 v[164:167], v247 offset:21504
	ds_read_b128 v[168:171], v247 offset:22528
	ds_read_b128 v[172:175], v247 offset:23552
	global_load_lds_dwordx4 v192, s[46:47]
	s_add_i32 m0, s74, 0x12000
	s_nop 0
	global_load_lds_dwordx4 v200, s[46:47]
	s_add_u32 s84, s46, 0x40000
	s_addc_u32 s85, s47, 0
	s_add_i32 m0, s74, 0x14000
	s_nop 0
	global_load_lds_dwordx4 v192, s[84:85]
	s_add_i32 m0, s74, 0x16000
	s_nop 0
	global_load_lds_dwordx4 v200, s[84:85]
	s_waitcnt vmcnt(4)
	s_waitcnt lgkmcnt(0)
	s_barrier
	v_mfma_f32_16x16x32_bf16 v[60:63], v[128:131], v[144:147], v[60:63]
	v_mfma_f32_16x16x32_bf16 v[56:59], v[136:139], v[144:147], v[56:59]
	v_mfma_f32_16x16x32_bf16 v[52:55], v[128:131], v[152:155], v[52:55]
	v_mfma_f32_16x16x32_bf16 v[48:51], v[136:139], v[152:155], v[48:51]
	v_mfma_f32_16x16x32_bf16 v[44:47], v[128:131], v[160:163], v[44:47]
	v_mfma_f32_16x16x32_bf16 v[40:43], v[136:139], v[160:163], v[40:43]
	v_mfma_f32_16x16x32_bf16 v[36:39], v[128:131], v[168:171], v[36:39]
	v_mfma_f32_16x16x32_bf16 v[32:35], v[136:139], v[168:171], v[32:35]
	v_mfma_f32_16x16x32_bf16 v[60:63], v[132:135], v[148:151], v[60:63]
	v_mfma_f32_16x16x32_bf16 v[56:59], v[140:143], v[148:151], v[56:59]
	v_mfma_f32_16x16x32_bf16 v[52:55], v[132:135], v[156:159], v[52:55]
	v_mfma_f32_16x16x32_bf16 v[48:51], v[140:143], v[156:159], v[48:51]
	v_mfma_f32_16x16x32_bf16 v[44:47], v[132:135], v[164:167], v[44:47]
	v_mfma_f32_16x16x32_bf16 v[40:43], v[140:143], v[164:167], v[40:43]
	v_mfma_f32_16x16x32_bf16 v[36:39], v[132:135], v[172:175], v[36:39]
	v_mfma_f32_16x16x32_bf16 v[32:35], v[140:143], v[172:175], v[32:35]
	v_mfma_f32_16x16x32_bf16 v[28:31], v[176:179], v[144:147], v[28:31]
	v_mfma_f32_16x16x32_bf16 v[24:27], v[184:187], v[144:147], v[24:27]
	v_mfma_f32_16x16x32_bf16 v[20:23], v[176:179], v[152:155], v[20:23]
	v_mfma_f32_16x16x32_bf16 v[16:19], v[184:187], v[152:155], v[16:19]
	v_mfma_f32_16x16x32_bf16 v[12:15], v[176:179], v[160:163], v[12:15]
	v_mfma_f32_16x16x32_bf16 v[8:11], v[184:187], v[160:163], v[8:11]
	v_mfma_f32_16x16x32_bf16 v[4:7], v[176:179], v[168:171], v[4:7]
	v_mfma_f32_16x16x32_bf16 v[0:3], v[184:187], v[168:171], v[0:3]
	v_mfma_f32_16x16x32_bf16 v[28:31], v[180:183], v[148:151], v[28:31]
	v_mfma_f32_16x16x32_bf16 v[24:27], v[188:191], v[148:151], v[24:27]
	v_mfma_f32_16x16x32_bf16 v[20:23], v[180:183], v[156:159], v[20:23]
	v_mfma_f32_16x16x32_bf16 v[16:19], v[188:191], v[156:159], v[16:19]
	v_mfma_f32_16x16x32_bf16 v[12:15], v[180:183], v[164:167], v[12:15]
	v_mfma_f32_16x16x32_bf16 v[8:11], v[188:191], v[164:167], v[8:11]
	v_mfma_f32_16x16x32_bf16 v[4:7], v[180:183], v[172:175], v[4:7]
	v_mfma_f32_16x16x32_bf16 v[0:3], v[188:191], v[172:175], v[0:3]
	s_barrier
; #define PG8_STAGE(bufoff, gbase, voff) do { _Pragma("unroll") for (int _i = 0; _i < 2; ++_i) \
;         __builtin_amdgcn_global_load_lds((const unsigned*)((const char*)(gbase) + (voff)[_i]), (LAS unsigned*)(lds + (bufoff) + ldsw + _i * 8192), 16, 0, 0); } while (0)
; #define PG8_LDA(dst, b, h) do { _Pragma("unroll") for (int m = 0; m < 4; ++m) _Pragma("unroll") for (int k = 0; k < 2; ++k) dst[m][k] = *(const LAS bf16x8*)(lds + PG8_SA(b, h) + aoff + m * 2048 + k * 1024); } while (0)
; #define PG8_LDB(dst, b, h) do { _Pragma("unroll") for (int n = 0; n < 2; ++n) _Pragma("unroll") for (int k = 0; k < 2; ++k) dst[n][k] = *(const LAS bf16x8*)(lds + PG8_SB(b, h) + boff + n * 2048 + k * 1024); } while (0)
; #define PG8_MMA(ai, bj, At, Bt) do { __builtin_amdgcn_s_setprio(1); _Pragma("unroll") for (int m = 0; m < 4; ++m) _Pragma("unroll") for (int n = 0; n < 2; ++n) _Pragma("unroll") for (int k = 0; k < 2; ++k) \
;         acc[ai][bj][m][n] = __builtin_amdgcn_mfma_f32_16x16x32_bf16(Bt[n][k], At[m][k], acc[ai][bj][m][n], 0, 0, 0); __builtin_amdgcn_s_setprio(0); } while (0)
; #define PG8_WAIT_V(n) asm volatile("s_waitcnt vmcnt(" #n ")" ::: "memory")
; #define PG8_WAIT_L(n) asm volatile("s_waitcnt lgkmcnt(" #n ")" ::: "memory")
; #define PG8_BAR __builtin_amdgcn_s_barrier()
; #define PG8_SCHED __builtin_amdgcn_sched_barrier(0)
; template <class Prog>
; __device__ __forceinline__ void gemm_phase(LAS unsigned char* lds, const int K, const Prog& S) {
;     ...
;             PG8_LDB(B0, 1, 0); PG8_SCHED; PG8_LDA(At, 1, 0); PG8_STAGE(PG8_SA(0, 1), a2 + hstep, voffA);
;             PG8_WAIT_L(8); PG8_BAR; PG8_WAIT_L(0); PG8_MMA(0, 0, At, B0); PG8_BAR; PG8_SCHED;
;             PG8_LDB(B1, 1, 1); PG8_STAGE(PG8_SB(1, 0), b3, voffB);
;             PG8_BAR; PG8_WAIT_L(0); PG8_MMA(0, 1, At, B1); PG8_BAR;
;             PG8_LDA(At, 1, 1); PG8_STAGE(PG8_SA(1, 0), a3, voffA);
;             PG8_BAR; PG8_WAIT_L(0); PG8_MMA(1, 0, At, B0); PG8_BAR; PG8_SCHED;
;             PG8_STAGE(PG8_SB(1, 1), b3 + hstep, voffB);
;             PG8_WAIT_V(6); PG8_BAR; PG8_MMA(1, 1, At, B1); PG8_BAR;
	s_add_u32 s84, s52, 0x40000
	s_addc_u32 s85, s53, 0
	ds_read_b128 v[128:131], v206 offset:32768
	ds_read_b128 v[132:135], v206 offset:33792
	ds_read_b128 v[136:139], v206 offset:34816
	ds_read_b128 v[140:143], v206 offset:35840
	s_mov_b32 m0, s74
	ds_read_b128 v[176:179], v206 offset:49152
	ds_read_b128 v[180:183], v206 offset:50176
	ds_read_b128 v[184:187], v206 offset:51200
	ds_read_b128 v[188:191], v206 offset:52224
	global_load_lds_dwordx4 v196, s[52:53]
	s_add_i32 m0, s74, 0x2000
	ds_read_b128 v[144:147], v247 offset:32768
	ds_read_b128 v[148:151], v247 offset:33792
	ds_read_b128 v[152:155], v247 offset:34816
	ds_read_b128 v[156:159], v247 offset:35840
	global_load_lds_dwordx4 v198, s[52:53]
	s_add_i32 m0, s74, 0x4000
	ds_read_b128 v[160:163], v247 offset:36864
	ds_read_b128 v[164:167], v247 offset:37888
	ds_read_b128 v[168:171], v247 offset:38912
	ds_read_b128 v[172:175], v247 offset:39936
	global_load_lds_dwordx4 v196, s[84:85]
	s_add_i32 m0, s74, 0x6000
	s_nop 0
	global_load_lds_dwordx4 v198, s[84:85]
	s_waitcnt lgkmcnt(0)
	s_barrier
	v_mfma_f32_16x16x32_bf16 v[124:127], v[128:131], v[144:147], v[124:127]
	v_mfma_f32_16x16x32_bf16 v[120:123], v[136:139], v[144:147], v[120:123]
	v_mfma_f32_16x16x32_bf16 v[116:119], v[128:131], v[152:155], v[116:119]
	v_mfma_f32_16x16x32_bf16 v[112:115], v[136:139], v[152:155], v[112:115]
	v_mfma_f32_16x16x32_bf16 v[108:111], v[128:131], v[160:163], v[108:111]
	v_mfma_f32_16x16x32_bf16 v[104:107], v[136:139], v[160:163], v[104:107]
	v_mfma_f32_16x16x32_bf16 v[100:103], v[128:131], v[168:171], v[100:103]
	v_mfma_f32_16x16x32_bf16 v[96:99], v[136:139], v[168:171], v[96:99]
	v_mfma_f32_16x16x32_bf16 v[124:127], v[132:135], v[148:151], v[124:127]
	v_mfma_f32_16x16x32_bf16 v[120:123], v[140:143], v[148:151], v[120:123]
	v_mfma_f32_16x16x32_bf16 v[116:119], v[132:135], v[156:159], v[116:119]
	v_mfma_f32_16x16x32_bf16 v[112:115], v[140:143], v[156:159], v[112:115]
	v_mfma_f32_16x16x32_bf16 v[108:111], v[132:135], v[164:167], v[108:111]
	v_mfma_f32_16x16x32_bf16 v[104:107], v[140:143], v[164:167], v[104:107]
	v_mfma_f32_16x16x32_bf16 v[100:103], v[132:135], v[172:175], v[100:103]
	v_mfma_f32_16x16x32_bf16 v[96:99], v[140:143], v[172:175], v[96:99]
	v_mfma_f32_16x16x32_bf16 v[92:95], v[176:179], v[144:147], v[92:95]
	v_mfma_f32_16x16x32_bf16 v[88:91], v[184:187], v[144:147], v[88:91]
	v_mfma_f32_16x16x32_bf16 v[84:87], v[176:179], v[152:155], v[84:87]
	v_mfma_f32_16x16x32_bf16 v[80:83], v[184:187], v[152:155], v[80:83]
	v_mfma_f32_16x16x32_bf16 v[76:79], v[176:179], v[160:163], v[76:79]
	v_mfma_f32_16x16x32_bf16 v[72:75], v[184:187], v[160:163], v[72:75]
	v_mfma_f32_16x16x32_bf16 v[68:71], v[176:179], v[168:171], v[68:71]
	v_mfma_f32_16x16x32_bf16 v[64:67], v[184:187], v[168:171], v[64:67]
	v_mfma_f32_16x16x32_bf16 v[92:95], v[180:183], v[148:151], v[92:95]
	v_mfma_f32_16x16x32_bf16 v[88:91], v[188:191], v[148:151], v[88:91]
	v_mfma_f32_16x16x32_bf16 v[84:87], v[180:183], v[156:159], v[84:87]
	v_mfma_f32_16x16x32_bf16 v[80:83], v[188:191], v[156:159], v[80:83]
	v_mfma_f32_16x16x32_bf16 v[76:79], v[180:183], v[164:167], v[76:79]
	v_mfma_f32_16x16x32_bf16 v[72:75], v[188:191], v[164:167], v[72:75]
	v_mfma_f32_16x16x32_bf16 v[68:71], v[180:183], v[172:175], v[68:71]
	v_mfma_f32_16x16x32_bf16 v[64:67], v[188:191], v[172:175], v[64:67]
	s_barrier
	s_add_u32 s84, s46, 0x80
	s_addc_u32 s85, s47, 0
	ds_read_b128 v[144:147], v247 offset:49152
	ds_read_b128 v[148:151], v247 offset:50176
	ds_read_b128 v[152:155], v247 offset:51200
	ds_read_b128 v[156:159], v247 offset:52224
	s_add_i32 m0, s74, 0x18000
	ds_read_b128 v[160:163], v247 offset:53248
	ds_read_b128 v[164:167], v247 offset:54272
	ds_read_b128 v[168:171], v247 offset:55296
	ds_read_b128 v[172:175], v247 offset:56320
	global_load_lds_dwordx4 v192, s[84:85]
	s_add_i32 m0, s74, 0x1a000
	s_nop 0
	global_load_lds_dwordx4 v200, s[84:85]
	s_add_u32 s84, s46, 0x40080
	s_addc_u32 s85, s47, 0
	s_add_i32 m0, s74, 0x1c000
	s_nop 0
	global_load_lds_dwordx4 v192, s[84:85]
	s_add_i32 m0, s74, 0x1e000
	s_nop 0
	global_load_lds_dwordx4 v200, s[84:85]
	s_waitcnt vmcnt(4)
	s_waitcnt lgkmcnt(0)
	s_barrier
	v_mfma_f32_16x16x32_bf16 v[60:63], v[128:131], v[144:147], v[60:63]
	v_mfma_f32_16x16x32_bf16 v[56:59], v[136:139], v[144:147], v[56:59]
	v_mfma_f32_16x16x32_bf16 v[52:55], v[128:131], v[152:155], v[52:55]
	v_mfma_f32_16x16x32_bf16 v[48:51], v[136:139], v[152:155], v[48:51]
	v_mfma_f32_16x16x32_bf16 v[44:47], v[128:131], v[160:163], v[44:47]
	v_mfma_f32_16x16x32_bf16 v[40:43], v[136:139], v[160:163], v[40:43]
	v_mfma_f32_16x16x32_bf16 v[36:39], v[128:131], v[168:171], v[36:39]
	v_mfma_f32_16x16x32_bf16 v[32:35], v[136:139], v[168:171], v[32:35]
	v_mfma_f32_16x16x32_bf16 v[60:63], v[132:135], v[148:151], v[60:63]
	v_mfma_f32_16x16x32_bf16 v[56:59], v[140:143], v[148:151], v[56:59]
	v_mfma_f32_16x16x32_bf16 v[52:55], v[132:135], v[156:159], v[52:55]
	v_mfma_f32_16x16x32_bf16 v[48:51], v[140:143], v[156:159], v[48:51]
	v_mfma_f32_16x16x32_bf16 v[44:47], v[132:135], v[164:167], v[44:47]
	v_mfma_f32_16x16x32_bf16 v[40:43], v[140:143], v[164:167], v[40:43]
	v_mfma_f32_16x16x32_bf16 v[36:39], v[132:135], v[172:175], v[36:39]
	v_mfma_f32_16x16x32_bf16 v[32:35], v[140:143], v[172:175], v[32:35]
	v_mfma_f32_16x16x32_bf16 v[28:31], v[176:179], v[144:147], v[28:31]
	v_mfma_f32_16x16x32_bf16 v[24:27], v[184:187], v[144:147], v[24:27]
	v_mfma_f32_16x16x32_bf16 v[20:23], v[176:179], v[152:155], v[20:23]
	v_mfma_f32_16x16x32_bf16 v[16:19], v[184:187], v[152:155], v[16:19]
	v_mfma_f32_16x16x32_bf16 v[12:15], v[176:179], v[160:163], v[12:15]
	v_mfma_f32_16x16x32_bf16 v[8:11], v[184:187], v[160:163], v[8:11]
	v_mfma_f32_16x16x32_bf16 v[4:7], v[176:179], v[168:171], v[4:7]
	v_mfma_f32_16x16x32_bf16 v[0:3], v[184:187], v[168:171], v[0:3]
	v_mfma_f32_16x16x32_bf16 v[28:31], v[180:183], v[148:151], v[28:31]
	v_mfma_f32_16x16x32_bf16 v[24:27], v[188:191], v[148:151], v[24:27]
	v_mfma_f32_16x16x32_bf16 v[20:23], v[180:183], v[156:159], v[20:23]
	v_mfma_f32_16x16x32_bf16 v[16:19], v[188:191], v[156:159], v[16:19]
	v_mfma_f32_16x16x32_bf16 v[12:15], v[180:183], v[164:167], v[12:15]
	v_mfma_f32_16x16x32_bf16 v[8:11], v[188:191], v[164:167], v[8:11]
	v_mfma_f32_16x16x32_bf16 v[4:7], v[180:183], v[172:175], v[4:7]
	v_mfma_f32_16x16x32_bf16 v[0:3], v[188:191], v[172:175], v[0:3]
	s_add_i32 s55, s55, 2
	s_add_u32 s44, s44, 0x100
	s_addc_u32 s45, s45, 0
	s_add_u32 s41, s41, 0x100
	s_addc_u32 s43, s43, 0
	s_cmp_gt_u32 s55, 13
	s_barrier
	s_cbranch_scc0 .LBB0_400
	s_cmpk_gt_u32 s62, 0xff
	s_cbranch_scc1 .Lrs_mg_b
	s_barrier
;     __device__ __forceinline__ void epi(f32x4 (&acc)[2][2][4][2], const pg8::Unit& u, int wr, int wc, int fr, int fq) const {
;         const int row0 = u.pm * 256 + wr * 64 + fr, col0 = u.pn * 256 + wc * 32 + 8 * fq;
;         const int sub = u.sub;
;         u32x4 gn[4][2][2], gd[4][2][2];
;         const int dsub = sub < 2 ? sub + 1 : sub;
;     ...
;         MG_LOAD(0); MG_LOAD(1);
.Lrs_mg_b:
	s_cmp_lt_i32 s14, 2
	v_lshl_add_u32 v208, s15, 8, v244
	v_lshl_or_b32 v206, s54, 8, v246
	s_cselect_b64 s[8:9], -1, 0
	s_cmp_gt_i32 s14, 1
	v_mov_b64_e32 v[128:129], s[26:27]
	s_cselect_b64 s[92:93], -1, 0
	s_cmp_lg_u64 s[8:9], 0
	v_ashrrev_i32_e32 v207, 31, v206
	v_mad_i64_i32 v[128:129], s[6:7], v208, s58, v[128:129]
	s_addc_u32 s15, s14, 0
	s_lshl_b32 s46, s14, 11
	v_lshl_add_u64 v[128:129], v[206:207], 1, v[128:129]
	s_ashr_i32 s47, s46, 31
	v_lshl_add_u64 v[128:129], v[128:129], 0, s[34:35]
	v_lshl_add_u64 v[130:131], s[46:47], 1, v[128:129]
	global_load_dwordx4 v[188:191], v[130:131], off
	s_lshl_b32 s52, s15, 11
	s_ashr_i32 s53, s52, 31
	v_mov_b32_e32 v148, 0
	s_and_b64 vcc, exec, s[92:93]
	v_lshl_add_u64 v[128:129], s[52:53], 1, v[128:129]
	v_mov_b32_e32 v180, 0
	v_mov_b32_e32 v181, 0
	v_mov_b32_e32 v182, 0
	v_mov_b32_e32 v183, 0
	s_cbranch_vccnz .LBB0_403
	global_load_dwordx4 v[180:183], v[128:129], off

; #define PG8_WAIT_V(n) asm volatile("s_waitcnt vmcnt(" #n ")" ::: "memory")
; #define PG8_BAR __builtin_amdgcn_s_barrier()
; template <class Prog>
; __device__ __forceinline__ void gemm_phase(LAS unsigned char* lds, const int K, const Prog& S) {
;     ...
;     PG8_WAIT_V(0);
;     if (wr == 0) PG8_BAR;
;     PG8_BAR;
.LBB0_501:
	s_waitcnt vmcnt(0)
	v_readlane_b32 s76, v254, 0
	v_readlane_b32 s78, v255, 11
	v_readlane_b32 s82, v255, 13
	v_readlane_b32 s84, v255, 15
	v_readlane_b32 s92, v255, 17
	v_readlane_b32 s94, v255, 19
	s_cmpk_gt_u32 s62, 0xff
	v_readlane_b32 s77, v254, 1
	v_readlane_b32 s79, v255, 12
	v_readlane_b32 s83, v255, 14
	v_readlane_b32 s85, v255, 16
	v_readlane_b32 s93, v255, 18
	v_readlane_b32 s95, v255, 20
	s_cbranch_scc1 .LBB0_503
.LBB0_503:
	v_readlane_b32 s72, v255, 21
	v_readlane_b32 s73, v255, 22
	s_mov_b32 s62, 0x3fb8aa3b
	v_readlane_b32 s69, v255, 26
	s_barrier

; #define PG8_STAGE(bufoff, gbase, voff) do { _Pragma("unroll") for (int _i = 0; _i < 2; ++_i) \
;         __builtin_amdgcn_global_load_lds((const unsigned*)((const char*)(gbase) + (voff)[_i]), (LAS unsigned*)(lds + (bufoff) + ldsw + _i * 8192), 16, 0, 0); } while (0)
; #define PG8_WAIT_V(n) asm volatile("s_waitcnt vmcnt(" #n ")" ::: "memory")
; #define PG8_BAR __builtin_amdgcn_s_barrier()
; template <class Prog>
; __device__ __forceinline__ void gemm_phase(LAS unsigned char* lds, const int K, const Prog& S) {
;     ...
;     const int tid = tid_, wid = __builtin_amdgcn_readfirstlane(tid >> 6), lane = tid & 63, wr = wid >> 2, wc = wid & 3, fr = lane & 15, fq = lane >> 4;
;     const int nt = K / BK;
;     unsigned voffA[2], voffB[2];
; #pragma unroll
;     for (int i = 0; i < 2; ++i) { int R, C; stage_rc(tid * 16 + i * 8192, R, C); const int Rb = Prog::PERM ? ((R & ~31) + perm32(R & 31)) : R;
;         voffA[i] = (unsigned)(R * K + C) * 2u; voffB[i] = (unsigned)(Rb * K + C) * 2u; }
;     const size_t kstep = (size_t)(BK * 2);
;     const size_t hstep = (size_t)HALF * K * 2;
;     const unsigned ldsw = (unsigned)wid * 1024u;
;     const int aoff = lds_byte(wr * 64 + fr, fq * 8), boff = lds_byte(wc * 32 + fr, fq * 8);
;     ...
;     Unit cur, nxt; int ui = 0;
;     if (!S.next(0, cur)) return;
;     f32x4 acc[2][2][4][2];
; #pragma unroll
;     for (int a = 0; a < 2; ++a)
; #pragma unroll
;         for (int b = 0; b < 2; ++b)
; #pragma unroll
;             for (int m = 0; m < 4; ++m)
; #pragma unroll
;                 for (int n = 0; n < 2; ++n) acc[a][b][m][n] = (f32x4){0.f, 0.f, 0.f, 0.f};
;     bf16x8 At[4][2], B0[2][2], B1[2][2];
;     const char* cA = cur.a; const char* cB = cur.b;
;     PG8_STAGE(PG8_SB(0, 0), cB, voffB); PG8_STAGE(PG8_SA(0, 0), cA, voffA); PG8_STAGE(PG8_SB(0, 1), cB + hstep, voffB); PG8_STAGE(PG8_SA(0, 1), cA + hstep, voffA);
;     if (wr == 1) PG8_BAR;
;     PG8_WAIT_V(4); PG8_BAR;
;     PG8_STAGE(PG8_SB(1, 0), cB + kstep, voffB); PG8_STAGE(PG8_SA(1, 0), cA + kstep, voffA); PG8_STAGE(PG8_SB(1, 1), cB + hstep + kstep, voffB);
;     PG8_WAIT_V(6); PG8_BAR;
;     __device__ __forceinline__ void epi(f32x4 (&acc)[2][2][4][2], const pg8::Unit& u, int wr, int wc, int fr, int fq) const {
;         const int row0 = u.pm * 256 + wr * 64 + fr, col0 = u.pn * 256 + wc * 32 + 4 * fq;
.LBB0_562:
	s_and_b64 vcc, exec, s[2:3]
	s_cbranch_vccnz .LBB0_670
	s_waitcnt lgkmcnt(0)
	v_ashrrev_i32_e32 v1, 31, v14
	v_lshrrev_b32_e32 v1, 26, v1
	v_add_u32_e32 v1, v14, v1
	v_ashrrev_i32_e32 v8, 6, v1
	v_bfe_i32 v1, v14, 27, 1
	v_lshlrev_b32_e32 v0, 4, v14
	v_lshrrev_b32_e32 v1, 22, v1
	v_add_u32_e32 v1, v0, v1
	v_and_b32_e32 v1, 0xfffffc00, v1
	v_sub_u32_e32 v1, v0, v1
	v_lshrrev_b32_e32 v2, 4, v1
	v_bitop3_b32 v1, v2, v1, 32 bitop3:0x6c
	v_ashrrev_i32_e32 v3, 31, v1
	v_lshrrev_b32_e32 v3, 26, v3
	v_add_u32_e32 v3, v1, v3
	v_ashrrev_i32_e32 v9, 6, v3
	v_and_b32_e32 v3, 0xc0, v3
	v_sub_u32_e32 v1, v1, v3
	v_lshlrev_b32_e32 v2, 3, v8
	v_lshlrev_b32_e32 v4, 5, v8
	v_ashrrev_i16_sdwa v1, v226, sext(v1) dst_sel:DWORD dst_unused:UNUSED_PAD src0_sel:DWORD src1_sel:BYTE_0
	v_and_b32_e32 v2, 0xffff0, v2
	v_and_b32_e32 v4, 32, v4
	v_bfe_i32 v10, v1, 0, 16
	v_add_u32_e32 v1, v4, v10
	v_add_lshl_u32 v2, v9, v2, 12
	v_add_u32_e32 v0, 0x2000, v0
	v_lshl_add_u32 v192, v1, 1, v2
	v_ashrrev_i32_e32 v1, 31, v0
	v_lshrrev_b32_e32 v1, 22, v1
	v_add_u32_e32 v1, v0, v1
	v_ashrrev_i32_e32 v11, 10, v1
	v_mul_i32_i24_e32 v1, 0x400, v11
	v_sub_u32_e32 v0, v0, v1
	v_lshrrev_b32_e32 v1, 4, v0
	v_bitop3_b32 v0, v1, v0, 32 bitop3:0x6c
	v_ashrrev_i32_e32 v2, 31, v0
	v_lshrrev_b32_e32 v2, 26, v2
	v_add_u32_e32 v2, v0, v2
	v_ashrrev_i32_e32 v12, 6, v2
	v_and_b32_e32 v2, 0xc0, v2
	s_ashr_i32 s2, s72, 6
	v_sub_u32_e32 v0, v0, v2
	v_lshlrev_b32_e32 v1, 3, v11
	v_lshlrev_b32_e32 v3, 5, v11
	v_ashrrev_i16_sdwa v0, v226, sext(v0) dst_sel:DWORD dst_unused:UNUSED_PAD src0_sel:DWORD src1_sel:BYTE_0
	s_lshl_b32 s74, s2, 10
	v_and_b32_e32 v1, 0xffff0, v1
	v_and_b32_e32 v3, 32, v3
	v_bfe_i32 v13, v0, 0, 16
	s_add_i32 s75, s74, 0
	v_add_u32_e32 v0, v3, v13
	v_add_lshl_u32 v1, v12, v1, 12
	s_add_i32 m0, s75, 0x10000
	v_lshl_add_u32 v188, v0, 1, v1
	global_load_lds_dwordx4 v192, s[52:53]
	s_add_i32 m0, s75, 0x12000
	s_ashr_i32 s3, s72, 8
	global_load_lds_dwordx4 v188, s[52:53]
	s_mov_b32 m0, s75
	s_add_i32 s76, s75, 0x2000
	global_load_lds_dwordx4 v192, s[46:47]
	s_mov_b32 m0, s76
	s_add_u32 s4, s52, 0x80000
	global_load_lds_dwordx4 v188, s[46:47]
	s_addc_u32 s5, s53, 0
	s_add_i32 m0, s75, 0x14000
	v_mov_b32_e32 v189, v193
	global_load_lds_dwordx4 v192, s[4:5]
	s_add_i32 m0, s75, 0x16000
	v_writelane_b32 v255, s69, 26
	global_load_lds_dwordx4 v188, s[4:5]
	s_add_u32 s4, s46, 0x80000
	s_addc_u32 s5, s47, 0
	s_add_i32 s77, s75, 0x4000
	s_mov_b32 m0, s77
	s_add_i32 s78, s75, 0x6000
	global_load_lds_dwordx4 v192, s[4:5]
	s_mov_b32 m0, s78
	v_lshl_add_u64 v[6:7], s[52:53], 0, v[192:193]
	global_load_lds_dwordx4 v188, s[4:5]
	v_readlane_b32 s4, v254, 4
	v_readlane_b32 s5, v254, 5
	s_load_dword s79, s[4:5], 0x0
	v_lshl_add_u64 v[4:5], s[52:53], 0, v[188:189]
	v_lshl_add_u64 v[2:3], s[46:47], 0, v[192:193]
	s_cmp_lg_u32 s3, 1
	v_lshl_add_u64 v[0:1], s[46:47], 0, v[188:189]
	s_cbranch_scc1 .LBB0_565
.LBB0_565:
	v_readlane_b32 s4, v255, 26
	s_cmp_eq_u32 s4, 0
	v_bfe_u32 v16, v14, 4, 2
	s_cselect_b32 s9, s17, s49
	s_cselect_b32 s8, s16, s48
	s_cmp_lg_u32 s4, 3
	v_and_b32_e32 v15, 15, v14
	v_lshlrev_b32_e32 v17, 4, v16
	v_lshlrev_b32_e32 v14, 2, v14
	s_cselect_b64 s[12:13], -1, 0
	s_and_b32 s15, s2, 3
	v_lshl_or_b32 v214, s3, 6, v15
	v_lshl_or_b32 v15, v15, 6, v17
	s_lshl_b32 s2, s3, 13
	v_and_b32_e32 v14, 32, v14
	s_add_i32 m0, s75, 0x18000
	v_lshl_add_u64 v[6:7], v[6:7], 0, s[96:97]
	v_bitop3_b32 v17, v15, s2, v14 bitop3:0xde
	s_lshl_b32 s2, s15, 12
	s_waitcnt vmcnt(0)
	s_barrier
	global_load_lds_dwordx4 v[6:7], off
	v_lshl_add_u64 v[4:5], v[4:5], 0, s[96:97]
	s_add_i32 m0, s75, 0x1a000
	s_add_i32 s69, s75, 0x8000
	s_add_i32 s84, s75, 0xa000
	v_bitop3_b32 v215, v15, s2, v14 bitop3:0xde
	global_load_lds_dwordx4 v[4:5], off
	v_lshl_add_u64 v[2:3], v[2:3], 0, s[96:97]
	s_mov_b32 m0, s69
	s_add_u32 s2, s52, 0x80080
	global_load_lds_dwordx4 v[2:3], off
	v_lshl_add_u64 v[0:1], v[0:1], 0, s[96:97]
	s_mov_b32 m0, s84
	s_addc_u32 s3, s53, 0
	global_load_lds_dwordx4 v[0:1], off
	s_add_i32 m0, s75, 0x1c000
	v_lshl_add_u64 v[0:1], s[2:3], 0, v[192:193]
	global_load_lds_dwordx4 v[0:1], off
	v_lshl_add_u64 v[0:1], s[2:3], 0, v[188:189]
	s_add_i32 m0, s75, 0x1e000
	s_mov_b32 s14, 0
	global_load_lds_dwordx4 v[0:1], off
	v_lshlrev_b32_e32 v0, 2, v16
	v_lshl_or_b32 v216, s15, 5, v0
	v_lshlrev_b32_e32 v0, 15, v8
	v_and_b32_e32 v0, 0xffff0000, v0
	v_lshl_add_u32 v0, v9, 12, v0
	v_and_b32_e32 v1, 1, v8
	v_lshl_or_b32 v0, v1, 6, v0
	v_lshl_add_u32 v190, v10, 1, v0
	v_lshlrev_b32_e32 v0, 15, v11
	v_and_b32_e32 v0, 0xffff0000, v0
	s_waitcnt vmcnt(6)
	v_lshl_add_u32 v0, v12, 12, v0
	v_and_b32_e32 v1, 1, v11
	v_lshl_or_b32 v0, v1, 6, v0
	v_cmp_eq_u32_e64 s[2:3], 0, v16
	s_waitcnt lgkmcnt(0)
	s_ashr_i32 s85, s79, 31
	v_mov_b32_e32 v191, v193
	v_lshl_add_u32 v196, v13, 1, v0
	v_mov_b32_e32 v197, v193
	v_add_u32_e32 v217, 0, v17
	s_barrier
	s_branch .LBB0_568

; template <class Prog>
; __device__ __forceinline__ void gemm_phase(LAS unsigned char* lds, const int K, const Prog& S) {
;     ...
;     for (;;) {
;         const bool has_next = S.next(ui + 1, nxt);
;         const char* nA = has_next ? nxt.a : cA; const char* nB = has_next ? nxt.b : cB;
;         for (int t = 0; t < nt; t += 2) {
.LBB0_570:
	s_cmpk_gt_u32 s72, 0xff
	s_cbranch_scc0 .Lrs_op_a
	s_barrier

; #define PG8_STAGE(bufoff, gbase, voff) do { _Pragma("unroll") for (int _i = 0; _i < 2; ++_i) \
;         __builtin_amdgcn_global_load_lds((const unsigned*)((const char*)(gbase) + (voff)[_i]), (LAS unsigned*)(lds + (bufoff) + ldsw + _i * 8192), 16, 0, 0); } while (0)
; #define PG8_LDA(dst, b, h) do { _Pragma("unroll") for (int m = 0; m < 4; ++m) _Pragma("unroll") for (int k = 0; k < 2; ++k) dst[m][k] = *(const LAS bf16x8*)(lds + PG8_SA(b, h) + aoff + m * 2048 + k * 1024); } while (0)
; #define PG8_LDB(dst, b, h) do { _Pragma("unroll") for (int n = 0; n < 2; ++n) _Pragma("unroll") for (int k = 0; k < 2; ++k) dst[n][k] = *(const LAS bf16x8*)(lds + PG8_SB(b, h) + boff + n * 2048 + k * 1024); } while (0)
; #define PG8_MMA(ai, bj, At, Bt) do { __builtin_amdgcn_s_setprio(1); _Pragma("unroll") for (int m = 0; m < 4; ++m) _Pragma("unroll") for (int n = 0; n < 2; ++n) _Pragma("unroll") for (int k = 0; k < 2; ++k) \
;         acc[ai][bj][m][n] = __builtin_amdgcn_mfma_f32_16x16x32_bf16(Bt[n][k], At[m][k], acc[ai][bj][m][n], 0, 0, 0); __builtin_amdgcn_s_setprio(0); } while (0)
; #define PG8_WAIT_V(n) asm volatile("s_waitcnt vmcnt(" #n ")" ::: "memory")
; #define PG8_WAIT_L(n) asm volatile("s_waitcnt lgkmcnt(" #n ")" ::: "memory")
; #define PG8_BAR __builtin_amdgcn_s_barrier()
; #define PG8_SCHED __builtin_amdgcn_sched_barrier(0)
; template <class Prog>
; __device__ __forceinline__ void gemm_phase(LAS unsigned char* lds, const int K, const Prog& S) {
;     ...
;             const bool last = (t == nt - 2);
;             const char* a1 = cA + (size_t)(t + 1) * kstep;
;             const char* a2 = last ? nA : cA + (size_t)(t + 2) * kstep; const char* b2 = last ? nB : cB + (size_t)(t + 2) * kstep;
;             const char* a3 = a2 + kstep; const char* b3 = b2 + kstep;
;             PG8_LDB(B0, 0, 0); PG8_SCHED; PG8_LDA(At, 0, 0); PG8_STAGE(PG8_SA(1, 1), a1 + hstep, voffA);
;             PG8_WAIT_L(8); PG8_BAR; PG8_WAIT_L(0); PG8_MMA(0, 0, At, B0); PG8_BAR; PG8_SCHED;
;             PG8_LDB(B1, 0, 1); PG8_STAGE(PG8_SB(0, 0), b2, voffB);
;             PG8_BAR; PG8_WAIT_L(0); PG8_MMA(0, 1, At, B1); PG8_BAR;
;             PG8_LDA(At, 0, 1); PG8_STAGE(PG8_SA(0, 0), a2, voffA);
;             PG8_BAR; PG8_WAIT_L(0); PG8_MMA(1, 0, At, B0); PG8_BAR; PG8_SCHED;
;             PG8_STAGE(PG8_SB(0, 1), b2 + hstep, voffB);
;             PG8_WAIT_V(6); PG8_BAR; PG8_MMA(1, 1, At, B1); PG8_BAR;
.LBB0_571:
	s_add_u32 s52, s46, 0xfff80080
	s_addc_u32 s53, s47, -1
	s_cmp_eq_u32 s54, 28
	s_cselect_b32 s93, s7, s53
	s_cselect_b32 s92, s6, s52
	s_cselect_b32 s53, s45, s43
	s_cselect_b32 s52, s44, s41
	s_add_u32 vcc_lo, s46, 0xfff80000
	s_addc_u32 vcc_hi, s47, -1
	ds_read_b128 v[128:131], v202
	ds_read_b128 v[132:135], v202 offset:1024
	ds_read_b128 v[136:139], v202 offset:2048
	ds_read_b128 v[140:143], v202 offset:3072
	s_add_i32 m0, s75, 0x8000
	ds_read_b128 v[176:179], v202 offset:16384
	ds_read_b128 v[180:183], v202 offset:17408
	ds_read_b128 v[184:187], v202 offset:18432
	ds_read_b128 v[198:201], v202 offset:19456
	global_load_lds_dwordx4 v190, vcc
	s_add_i32 m0, s75, 0xa000
	ds_read_b128 v[144:147], v217
	ds_read_b128 v[148:151], v217 offset:1024
	ds_read_b128 v[152:155], v217 offset:2048
	ds_read_b128 v[156:159], v217 offset:3072
	global_load_lds_dwordx4 v196, vcc
	s_add_i32 m0, s75, 0xc000
	ds_read_b128 v[160:163], v217 offset:4096
	ds_read_b128 v[164:167], v217 offset:5120
	ds_read_b128 v[168:171], v217 offset:6144
	ds_read_b128 v[172:175], v217 offset:7168
	global_load_lds_dwordx4 v190, s[46:47]
	s_add_i32 m0, s75, 0xe000
	s_nop 0
	global_load_lds_dwordx4 v196, s[46:47]
	s_waitcnt lgkmcnt(0)
	s_barrier
	v_mfma_f32_16x16x32_bf16 v[124:127], v[128:131], v[144:147], v[124:127]
	v_mfma_f32_16x16x32_bf16 v[120:123], v[136:139], v[144:147], v[120:123]
	v_mfma_f32_16x16x32_bf16 v[108:111], v[128:131], v[152:155], v[108:111]
	v_mfma_f32_16x16x32_bf16 v[104:107], v[136:139], v[152:155], v[104:107]
	v_mfma_f32_16x16x32_bf16 v[92:95], v[128:131], v[160:163], v[92:95]
	v_mfma_f32_16x16x32_bf16 v[88:91], v[136:139], v[160:163], v[88:91]
	v_mfma_f32_16x16x32_bf16 v[76:79], v[128:131], v[168:171], v[76:79]
	v_mfma_f32_16x16x32_bf16 v[72:75], v[136:139], v[168:171], v[72:75]
	v_mfma_f32_16x16x32_bf16 v[124:127], v[132:135], v[148:151], v[124:127]
	v_mfma_f32_16x16x32_bf16 v[120:123], v[140:143], v[148:151], v[120:123]
	v_mfma_f32_16x16x32_bf16 v[108:111], v[132:135], v[156:159], v[108:111]
	v_mfma_f32_16x16x32_bf16 v[104:107], v[140:143], v[156:159], v[104:107]
	v_mfma_f32_16x16x32_bf16 v[92:95], v[132:135], v[164:167], v[92:95]
	v_mfma_f32_16x16x32_bf16 v[88:91], v[140:143], v[164:167], v[88:91]
	v_mfma_f32_16x16x32_bf16 v[76:79], v[132:135], v[172:175], v[76:79]
	v_mfma_f32_16x16x32_bf16 v[72:75], v[140:143], v[172:175], v[72:75]
	v_mfma_f32_16x16x32_bf16 v[116:119], v[176:179], v[144:147], v[116:119]
	v_mfma_f32_16x16x32_bf16 v[112:115], v[184:187], v[144:147], v[112:115]
	v_mfma_f32_16x16x32_bf16 v[100:103], v[176:179], v[152:155], v[100:103]
	v_mfma_f32_16x16x32_bf16 v[96:99], v[184:187], v[152:155], v[96:99]
	v_mfma_f32_16x16x32_bf16 v[84:87], v[176:179], v[160:163], v[84:87]
	v_mfma_f32_16x16x32_bf16 v[80:83], v[184:187], v[160:163], v[80:83]
	v_mfma_f32_16x16x32_bf16 v[68:71], v[176:179], v[168:171], v[68:71]
	v_mfma_f32_16x16x32_bf16 v[64:67], v[184:187], v[168:171], v[64:67]
	v_mfma_f32_16x16x32_bf16 v[116:119], v[180:183], v[148:151], v[116:119]
	v_mfma_f32_16x16x32_bf16 v[112:115], v[198:201], v[148:151], v[112:115]
	v_mfma_f32_16x16x32_bf16 v[100:103], v[180:183], v[156:159], v[100:103]
	v_mfma_f32_16x16x32_bf16 v[96:99], v[198:201], v[156:159], v[96:99]
	v_mfma_f32_16x16x32_bf16 v[84:87], v[180:183], v[164:167], v[84:87]
	v_mfma_f32_16x16x32_bf16 v[80:83], v[198:201], v[164:167], v[80:83]
	v_mfma_f32_16x16x32_bf16 v[68:71], v[180:183], v[172:175], v[68:71]
	v_mfma_f32_16x16x32_bf16 v[64:67], v[198:201], v[172:175], v[64:67]
	s_barrier
	ds_read_b128 v[144:147], v217 offset:16384
	ds_read_b128 v[148:151], v217 offset:17408
	ds_read_b128 v[152:155], v217 offset:18432
	ds_read_b128 v[156:159], v217 offset:19456
	s_add_i32 m0, s75, 0x10000
	ds_read_b128 v[160:163], v217 offset:20480
	ds_read_b128 v[164:167], v217 offset:21504
	ds_read_b128 v[168:171], v217 offset:22528
	ds_read_b128 v[172:175], v217 offset:23552
	global_load_lds_dwordx4 v192, s[52:53]
	s_add_i32 m0, s75, 0x12000
	s_nop 0
	global_load_lds_dwordx4 v188, s[52:53]
	s_add_u32 vcc_lo, s52, 0x80000
	s_addc_u32 vcc_hi, s53, 0
	s_add_i32 m0, s75, 0x14000
	s_nop 0
	global_load_lds_dwordx4 v192, vcc
	s_add_i32 m0, s75, 0x16000
	s_nop 0
	global_load_lds_dwordx4 v188, vcc
	s_waitcnt vmcnt(4)
	s_waitcnt lgkmcnt(0)
	s_barrier
	v_mfma_f32_16x16x32_bf16 v[60:63], v[128:131], v[144:147], v[60:63]
	v_mfma_f32_16x16x32_bf16 v[56:59], v[136:139], v[144:147], v[56:59]
	v_mfma_f32_16x16x32_bf16 v[44:47], v[128:131], v[152:155], v[44:47]
	v_mfma_f32_16x16x32_bf16 v[40:43], v[136:139], v[152:155], v[40:43]
	v_mfma_f32_16x16x32_bf16 v[28:31], v[128:131], v[160:163], v[28:31]
	v_mfma_f32_16x16x32_bf16 v[24:27], v[136:139], v[160:163], v[24:27]
	v_mfma_f32_16x16x32_bf16 v[12:15], v[128:131], v[168:171], v[12:15]
	v_mfma_f32_16x16x32_bf16 v[8:11], v[136:139], v[168:171], v[8:11]
	v_mfma_f32_16x16x32_bf16 v[60:63], v[132:135], v[148:151], v[60:63]
	v_mfma_f32_16x16x32_bf16 v[56:59], v[140:143], v[148:151], v[56:59]
	v_mfma_f32_16x16x32_bf16 v[44:47], v[132:135], v[156:159], v[44:47]
	v_mfma_f32_16x16x32_bf16 v[40:43], v[140:143], v[156:159], v[40:43]
	v_mfma_f32_16x16x32_bf16 v[28:31], v[132:135], v[164:167], v[28:31]
	v_mfma_f32_16x16x32_bf16 v[24:27], v[140:143], v[164:167], v[24:27]
	v_mfma_f32_16x16x32_bf16 v[12:15], v[132:135], v[172:175], v[12:15]
	v_mfma_f32_16x16x32_bf16 v[8:11], v[140:143], v[172:175], v[8:11]
	v_mfma_f32_16x16x32_bf16 v[52:55], v[176:179], v[144:147], v[52:55]
	v_mfma_f32_16x16x32_bf16 v[48:51], v[184:187], v[144:147], v[48:51]
	v_mfma_f32_16x16x32_bf16 v[36:39], v[176:179], v[152:155], v[36:39]
	v_mfma_f32_16x16x32_bf16 v[32:35], v[184:187], v[152:155], v[32:35]
	v_mfma_f32_16x16x32_bf16 v[20:23], v[176:179], v[160:163], v[20:23]
	v_mfma_f32_16x16x32_bf16 v[16:19], v[184:187], v[160:163], v[16:19]
	v_mfma_f32_16x16x32_bf16 v[4:7], v[176:179], v[168:171], v[4:7]
	v_mfma_f32_16x16x32_bf16 v[0:3], v[184:187], v[168:171], v[0:3]
	v_mfma_f32_16x16x32_bf16 v[52:55], v[180:183], v[148:151], v[52:55]
	v_mfma_f32_16x16x32_bf16 v[48:51], v[198:201], v[148:151], v[48:51]
	v_mfma_f32_16x16x32_bf16 v[36:39], v[180:183], v[156:159], v[36:39]
	v_mfma_f32_16x16x32_bf16 v[32:35], v[198:201], v[156:159], v[32:35]
	v_mfma_f32_16x16x32_bf16 v[20:23], v[180:183], v[164:167], v[20:23]
	v_mfma_f32_16x16x32_bf16 v[16:19], v[198:201], v[164:167], v[16:19]
	v_mfma_f32_16x16x32_bf16 v[4:7], v[180:183], v[172:175], v[4:7]
	v_mfma_f32_16x16x32_bf16 v[0:3], v[198:201], v[172:175], v[0:3]
	s_barrier
; #define PG8_STAGE(bufoff, gbase, voff) do { _Pragma("unroll") for (int _i = 0; _i < 2; ++_i) \
;         __builtin_amdgcn_global_load_lds((const unsigned*)((const char*)(gbase) + (voff)[_i]), (LAS unsigned*)(lds + (bufoff) + ldsw + _i * 8192), 16, 0, 0); } while (0)
; #define PG8_LDA(dst, b, h) do { _Pragma("unroll") for (int m = 0; m < 4; ++m) _Pragma("unroll") for (int k = 0; k < 2; ++k) dst[m][k] = *(const LAS bf16x8*)(lds + PG8_SA(b, h) + aoff + m * 2048 + k * 1024); } while (0)
; #define PG8_LDB(dst, b, h) do { _Pragma("unroll") for (int n = 0; n < 2; ++n) _Pragma("unroll") for (int k = 0; k < 2; ++k) dst[n][k] = *(const LAS bf16x8*)(lds + PG8_SB(b, h) + boff + n * 2048 + k * 1024); } while (0)
; #define PG8_MMA(ai, bj, At, Bt) do { __builtin_amdgcn_s_setprio(1); _Pragma("unroll") for (int m = 0; m < 4; ++m) _Pragma("unroll") for (int n = 0; n < 2; ++n) _Pragma("unroll") for (int k = 0; k < 2; ++k) \
;         acc[ai][bj][m][n] = __builtin_amdgcn_mfma_f32_16x16x32_bf16(Bt[n][k], At[m][k], acc[ai][bj][m][n], 0, 0, 0); __builtin_amdgcn_s_setprio(0); } while (0)
; #define PG8_WAIT_V(n) asm volatile("s_waitcnt vmcnt(" #n ")" ::: "memory")
; #define PG8_WAIT_L(n) asm volatile("s_waitcnt lgkmcnt(" #n ")" ::: "memory")
; #define PG8_BAR __builtin_amdgcn_s_barrier()
; #define PG8_SCHED __builtin_amdgcn_sched_barrier(0)
; template <class Prog>
; __device__ __forceinline__ void gemm_phase(LAS unsigned char* lds, const int K, const Prog& S) {
;     ...
;             PG8_LDB(B0, 1, 0); PG8_SCHED; PG8_LDA(At, 1, 0); PG8_STAGE(PG8_SA(0, 1), a2 + hstep, voffA);
;             PG8_WAIT_L(8); PG8_BAR; PG8_WAIT_L(0); PG8_MMA(0, 0, At, B0); PG8_BAR; PG8_SCHED;
;             PG8_LDB(B1, 1, 1); PG8_STAGE(PG8_SB(1, 0), b3, voffB);
;             PG8_BAR; PG8_WAIT_L(0); PG8_MMA(0, 1, At, B1); PG8_BAR;
;             PG8_LDA(At, 1, 1); PG8_STAGE(PG8_SA(1, 0), a3, voffA);
;             PG8_BAR; PG8_WAIT_L(0); PG8_MMA(1, 0, At, B0); PG8_BAR; PG8_SCHED;
;             PG8_STAGE(PG8_SB(1, 1), b3 + hstep, voffB);
;             PG8_WAIT_V(6); PG8_BAR; PG8_MMA(1, 1, At, B1); PG8_BAR;
	s_add_u32 vcc_lo, s92, 0x80000
	s_addc_u32 vcc_hi, s93, 0
	ds_read_b128 v[128:131], v202 offset:32768
	ds_read_b128 v[132:135], v202 offset:33792
	ds_read_b128 v[136:139], v202 offset:34816
	ds_read_b128 v[140:143], v202 offset:35840
	s_mov_b32 m0, s75
	ds_read_b128 v[176:179], v202 offset:49152
	ds_read_b128 v[180:183], v202 offset:50176
	ds_read_b128 v[184:187], v202 offset:51200
	ds_read_b128 v[198:201], v202 offset:52224
	global_load_lds_dwordx4 v192, s[92:93]
	s_add_i32 m0, s75, 0x2000
	ds_read_b128 v[144:147], v217 offset:32768
	ds_read_b128 v[148:151], v217 offset:33792
	ds_read_b128 v[152:155], v217 offset:34816
	ds_read_b128 v[156:159], v217 offset:35840
	global_load_lds_dwordx4 v188, s[92:93]
	s_add_i32 m0, s75, 0x4000
	ds_read_b128 v[160:163], v217 offset:36864
	ds_read_b128 v[164:167], v217 offset:37888
	ds_read_b128 v[168:171], v217 offset:38912
	ds_read_b128 v[172:175], v217 offset:39936
	global_load_lds_dwordx4 v192, vcc
	s_add_i32 m0, s75, 0x6000
	s_nop 0
	global_load_lds_dwordx4 v188, vcc
	s_waitcnt lgkmcnt(0)
	s_barrier
	v_mfma_f32_16x16x32_bf16 v[124:127], v[128:131], v[144:147], v[124:127]
	v_mfma_f32_16x16x32_bf16 v[120:123], v[136:139], v[144:147], v[120:123]
	v_mfma_f32_16x16x32_bf16 v[108:111], v[128:131], v[152:155], v[108:111]
	v_mfma_f32_16x16x32_bf16 v[104:107], v[136:139], v[152:155], v[104:107]
	v_mfma_f32_16x16x32_bf16 v[92:95], v[128:131], v[160:163], v[92:95]
	v_mfma_f32_16x16x32_bf16 v[88:91], v[136:139], v[160:163], v[88:91]
	v_mfma_f32_16x16x32_bf16 v[76:79], v[128:131], v[168:171], v[76:79]
	v_mfma_f32_16x16x32_bf16 v[72:75], v[136:139], v[168:171], v[72:75]
	v_mfma_f32_16x16x32_bf16 v[124:127], v[132:135], v[148:151], v[124:127]
	v_mfma_f32_16x16x32_bf16 v[120:123], v[140:143], v[148:151], v[120:123]
	v_mfma_f32_16x16x32_bf16 v[108:111], v[132:135], v[156:159], v[108:111]
	v_mfma_f32_16x16x32_bf16 v[104:107], v[140:143], v[156:159], v[104:107]
	v_mfma_f32_16x16x32_bf16 v[92:95], v[132:135], v[164:167], v[92:95]
	v_mfma_f32_16x16x32_bf16 v[88:91], v[140:143], v[164:167], v[88:91]
	v_mfma_f32_16x16x32_bf16 v[76:79], v[132:135], v[172:175], v[76:79]
	v_mfma_f32_16x16x32_bf16 v[72:75], v[140:143], v[172:175], v[72:75]
	v_mfma_f32_16x16x32_bf16 v[116:119], v[176:179], v[144:147], v[116:119]
	v_mfma_f32_16x16x32_bf16 v[112:115], v[184:187], v[144:147], v[112:115]
	v_mfma_f32_16x16x32_bf16 v[100:103], v[176:179], v[152:155], v[100:103]
	v_mfma_f32_16x16x32_bf16 v[96:99], v[184:187], v[152:155], v[96:99]
	v_mfma_f32_16x16x32_bf16 v[84:87], v[176:179], v[160:163], v[84:87]
	v_mfma_f32_16x16x32_bf16 v[80:83], v[184:187], v[160:163], v[80:83]
	v_mfma_f32_16x16x32_bf16 v[68:71], v[176:179], v[168:171], v[68:71]
	v_mfma_f32_16x16x32_bf16 v[64:67], v[184:187], v[168:171], v[64:67]
	v_mfma_f32_16x16x32_bf16 v[116:119], v[180:183], v[148:151], v[116:119]
	v_mfma_f32_16x16x32_bf16 v[112:115], v[198:201], v[148:151], v[112:115]
	v_mfma_f32_16x16x32_bf16 v[100:103], v[180:183], v[156:159], v[100:103]
	v_mfma_f32_16x16x32_bf16 v[96:99], v[198:201], v[156:159], v[96:99]
	v_mfma_f32_16x16x32_bf16 v[84:87], v[180:183], v[164:167], v[84:87]
	v_mfma_f32_16x16x32_bf16 v[80:83], v[198:201], v[164:167], v[80:83]
	v_mfma_f32_16x16x32_bf16 v[68:71], v[180:183], v[172:175], v[68:71]
	v_mfma_f32_16x16x32_bf16 v[64:67], v[198:201], v[172:175], v[64:67]
	s_barrier
	s_add_u32 vcc_lo, s52, 0x80
	s_addc_u32 vcc_hi, s53, 0
	ds_read_b128 v[144:147], v217 offset:49152
	ds_read_b128 v[148:151], v217 offset:50176
	ds_read_b128 v[152:155], v217 offset:51200
	ds_read_b128 v[156:159], v217 offset:52224
	s_add_i32 m0, s75, 0x18000
	ds_read_b128 v[160:163], v217 offset:53248
	ds_read_b128 v[164:167], v217 offset:54272
	ds_read_b128 v[168:171], v217 offset:55296
	ds_read_b128 v[172:175], v217 offset:56320
	global_load_lds_dwordx4 v192, vcc
	s_add_i32 m0, s75, 0x1a000
	s_nop 0
	global_load_lds_dwordx4 v188, vcc
	s_add_u32 vcc_lo, s52, 0x80080
	s_addc_u32 vcc_hi, s53, 0
	s_add_i32 m0, s75, 0x1c000
	s_nop 0
	global_load_lds_dwordx4 v192, vcc
	s_add_i32 m0, s75, 0x1e000
	s_nop 0
	global_load_lds_dwordx4 v188, vcc
	s_waitcnt vmcnt(4)
	s_waitcnt lgkmcnt(0)
	s_barrier
	v_mfma_f32_16x16x32_bf16 v[60:63], v[128:131], v[144:147], v[60:63]
	v_mfma_f32_16x16x32_bf16 v[56:59], v[136:139], v[144:147], v[56:59]
	v_mfma_f32_16x16x32_bf16 v[44:47], v[128:131], v[152:155], v[44:47]
	v_mfma_f32_16x16x32_bf16 v[40:43], v[136:139], v[152:155], v[40:43]
	v_mfma_f32_16x16x32_bf16 v[28:31], v[128:131], v[160:163], v[28:31]
	v_mfma_f32_16x16x32_bf16 v[24:27], v[136:139], v[160:163], v[24:27]
	v_mfma_f32_16x16x32_bf16 v[12:15], v[128:131], v[168:171], v[12:15]
	v_mfma_f32_16x16x32_bf16 v[8:11], v[136:139], v[168:171], v[8:11]
	v_mfma_f32_16x16x32_bf16 v[60:63], v[132:135], v[148:151], v[60:63]
	v_mfma_f32_16x16x32_bf16 v[56:59], v[140:143], v[148:151], v[56:59]
	v_mfma_f32_16x16x32_bf16 v[44:47], v[132:135], v[156:159], v[44:47]
	v_mfma_f32_16x16x32_bf16 v[40:43], v[140:143], v[156:159], v[40:43]
	v_mfma_f32_16x16x32_bf16 v[28:31], v[132:135], v[164:167], v[28:31]
	v_mfma_f32_16x16x32_bf16 v[24:27], v[140:143], v[164:167], v[24:27]
	v_mfma_f32_16x16x32_bf16 v[12:15], v[132:135], v[172:175], v[12:15]
	v_mfma_f32_16x16x32_bf16 v[8:11], v[140:143], v[172:175], v[8:11]
	v_mfma_f32_16x16x32_bf16 v[52:55], v[176:179], v[144:147], v[52:55]
	v_mfma_f32_16x16x32_bf16 v[48:51], v[184:187], v[144:147], v[48:51]
	v_mfma_f32_16x16x32_bf16 v[36:39], v[176:179], v[152:155], v[36:39]
	v_mfma_f32_16x16x32_bf16 v[32:35], v[184:187], v[152:155], v[32:35]
	v_mfma_f32_16x16x32_bf16 v[20:23], v[176:179], v[160:163], v[20:23]
	v_mfma_f32_16x16x32_bf16 v[16:19], v[184:187], v[160:163], v[16:19]
	v_mfma_f32_16x16x32_bf16 v[4:7], v[176:179], v[168:171], v[4:7]
	v_mfma_f32_16x16x32_bf16 v[0:3], v[184:187], v[168:171], v[0:3]
	v_mfma_f32_16x16x32_bf16 v[52:55], v[180:183], v[148:151], v[52:55]
	v_mfma_f32_16x16x32_bf16 v[48:51], v[198:201], v[148:151], v[48:51]
	v_mfma_f32_16x16x32_bf16 v[36:39], v[180:183], v[156:159], v[36:39]
	v_mfma_f32_16x16x32_bf16 v[32:35], v[198:201], v[156:159], v[32:35]
	v_mfma_f32_16x16x32_bf16 v[20:23], v[180:183], v[164:167], v[20:23]
	v_mfma_f32_16x16x32_bf16 v[16:19], v[198:201], v[164:167], v[16:19]
	v_mfma_f32_16x16x32_bf16 v[4:7], v[180:183], v[172:175], v[4:7]
	v_mfma_f32_16x16x32_bf16 v[0:3], v[198:201], v[172:175], v[0:3]
	s_add_i32 s54, s54, 2
	s_add_u32 s46, s46, 0x100
	s_addc_u32 s47, s47, 0
	s_add_u32 s41, s41, 0x100
	s_addc_u32 s43, s43, 0
	s_cmp_gt_u32 s54, 29
	s_barrier
	s_cbranch_scc0 .LBB0_571
	s_cmpk_gt_u32 s72, 0xff
	s_cbranch_scc1 .Lrs_op_b
	s_barrier
; __device__ __forceinline__ unsigned cvt_pk_bf16(float lo, float hi) { unsigned r; asm volatile("v_cvt_pk_bf16_f32 %0, %1, %2" : "=v"(r) : "v"(lo), "v"(hi)); return r; }
;     __device__ __forceinline__ void epi(f32x4 (&acc)[2][2][4][2], const pg8::Unit& u, int wr, int wc, int fr, int fq) const {
;         const int row0 = u.pm * 256 + wr * 64 + fr, col0 = u.pn * 256 + wc * 32 + 4 * fq;
; #pragma unroll
;         for (int ai = 0; ai < 2; ++ai) {
;             f32x4 xo[4][2][2];
; #pragma unroll
;             for (int m = 0; m < 4; ++m)
; #pragma unroll
;                 for (int bj = 0; bj < 2; ++bj)
; #pragma unroll
;                     for (int n = 0; n < 2; ++n) xo[m][bj][n] = *(const f32x4*)(xin + (size_t)(row0 + ai * 128 + m * 16) * DM + col0 + bj * 128 + n * 16);
; #pragma unroll
;             for (int m = 0; m < 4; ++m) {
;                 const int row = row0 + ai * 128 + m * 16;
;                 const size_t off = (size_t)row * DM + col0;
;                 float ss = 0.f;
; #pragma unroll
;                 for (int bj = 0; bj < 2; ++bj)
; #pragma unroll
;                     for (int n = 0; n < 2; ++n) {
;                         const f32x4 o = xo[m][bj][n] + acc[ai][bj][m][n];
;                         *(f32x4*)(xout + off + bj * 128 + n * 16) = o;
;                         ss += o[0] * o[0] + o[1] * o[1] + o[2] * o[2] + o[3] * o[3];
;                         if (rowss_next) { u32x2 w; w.x = cvt_pk_bf16(o[0], o[1]); w.y = cvt_pk_bf16(o[2], o[3]); *(u32x2*)(xb + off + bj * 128 + n * 16) = w; }
.Lrs_op_b:
	v_lshl_add_u32 v202, s80, 8, v214
	v_lshl_or_b32 v198, s73, 8, v216
	v_ashrrev_i32_e32 v199, 31, v198
	v_ashrrev_i32_e32 v203, 31, v202
	v_lshl_add_u64 v[200:201], v[198:199], 2, s[8:9]
	v_lshlrev_b64 v[128:129], 13, v[202:203]
	v_or_b32_e32 v208, 16, v202
	v_lshl_add_u64 v[128:129], v[200:201], 0, v[128:129]
	v_ashrrev_i32_e32 v209, 31, v208
	global_load_dwordx4 v[210:213], v[128:129], off
	global_load_dwordx4 v[184:187], v[128:129], off offset:64
	global_load_dwordx4 v[180:183], v[128:129], off offset:512
	global_load_dwordx4 v[176:179], v[128:129], off offset:576
	v_lshlrev_b64 v[128:129], 13, v[208:209]
	v_or_b32_e32 v206, 32, v202
	v_lshl_add_u64 v[128:129], v[200:201], 0, v[128:129]
	v_ashrrev_i32_e32 v207, 31, v206
	global_load_dwordx4 v[172:175], v[128:129], off
	global_load_dwordx4 v[168:171], v[128:129], off offset:64
	global_load_dwordx4 v[164:167], v[128:129], off offset:512
	global_load_dwordx4 v[160:163], v[128:129], off offset:576
	v_lshlrev_b64 v[128:129], 13, v[206:207]
	v_or_b32_e32 v204, 48, v202
	v_lshl_add_u64 v[128:129], v[200:201], 0, v[128:129]
	v_ashrrev_i32_e32 v205, 31, v204
	global_load_dwordx4 v[156:159], v[128:129], off
	global_load_dwordx4 v[152:155], v[128:129], off offset:64
	global_load_dwordx4 v[148:151], v[128:129], off offset:512
	global_load_dwordx4 v[144:147], v[128:129], off offset:576
	v_lshlrev_b64 v[128:129], 13, v[204:205]
	v_lshl_add_u64 v[128:129], v[200:201], 0, v[128:129]
	global_load_dwordx4 v[140:143], v[128:129], off
	global_load_dwordx4 v[136:139], v[128:129], off offset:64
	global_load_dwordx4 v[132:135], v[128:129], off offset:512
	s_nop 0
	global_load_dwordx4 v[128:131], v[128:129], off offset:576
	v_lshlrev_b64 v[218:219], 11, v[202:203]
	v_lshl_add_u64 v[218:219], v[218:219], 0, v[198:199]
	s_andn2_b64 vcc, exec, s[12:13]
	s_waitcnt vmcnt(0)
	v_pk_add_f32 v[126:127], v[126:127], v[212:213]
	v_cndmask_b32_e64 v212, 0, 1, s[12:13]
	v_pk_add_f32 v[124:125], v[124:125], v[210:211]
	v_lshl_add_u64 v[210:211], v[218:219], 2, s[48:49]
	v_cmp_ne_u32_e64 s[6:7], 1, v212
	v_lshl_add_u64 v[212:213], v[218:219], 1, s[20:21]
	global_store_dwordx4 v[210:211], v[124:127], off
	s_cbranch_vccnz .LBB0_574
	v_cvt_pk_bf16_f32 v218, v124, v125
	v_cvt_pk_bf16_f32 v219, v126, v127
	global_store_dwordx2 v[212:213], v[218:219], off

; #define PG8_WAIT_V(n) asm volatile("s_waitcnt vmcnt(" #n ")" ::: "memory")
; #define PG8_BAR __builtin_amdgcn_s_barrier()
; template <class Prog>
; __device__ __forceinline__ void gemm_phase(LAS unsigned char* lds, const int K, const Prog& S) {
;     ...
;     PG8_WAIT_V(0);
;     if (wr == 0) PG8_BAR;
;     PG8_BAR;
.LBB0_667:
	s_waitcnt vmcnt(0)
	v_readlane_b32 s76, v254, 0
	v_readlane_b32 s78, v255, 11
	v_readlane_b32 s82, v255, 13
	v_readlane_b32 s84, v255, 15
	v_readlane_b32 s92, v255, 17
	v_readlane_b32 s94, v255, 19
	s_cmpk_gt_u32 s72, 0xff
	v_readlane_b32 s77, v254, 1
	v_readlane_b32 s79, v255, 12
	v_readlane_b32 s83, v255, 14
	v_readlane_b32 s85, v255, 16
	v_readlane_b32 s93, v255, 18
	v_readlane_b32 s95, v255, 20
	s_cbranch_scc1 .LBB0_669
.LBB0_669:
	s_mov_b32 s62, 0x3fb8aa3b
	v_readlane_b32 s69, v255, 26
	s_barrier
